# peer_q GEMM gets the same k-loop structure (weight keys tile by LDS-DMA double buffer, token tile register-staged two k-steps ahead); all three GEMM phases now
# speedup vs baseline: 1.0450x; 1.0109x over previous
;   DI u16* hb() const { return (u16*)(ws + OFF_hb); }
; #define tid_opaque() tid_from(WAVE_S)
;   const int tid = tid_opaque(), lane = tid & 63;
;   u16* Xs = lds;
;   u16* Ys = lds + 128 * LSTR;
;   const int lr = tid >> 3, lc = (tid & 7) * 8;
;   const u16* xg = X + (size_t)lr * RS + lc;
;   const u16* yg = Y + (size_t)lr * RS + lc;
;   u32x4 xr[4], yr[4];
; #pragma unroll
;   for (int it = 0; it < 4; ++it) {
;     xr[it] = *(const u32x4*)(xg + (size_t)it * 32 * RS);
;     yr[it] = *(const u32x4*)(yg + (size_t)it * 32 * RS);
;   }
; #pragma unroll
;   for (int a = 0; a < TI; ++a)
; #pragma unroll
;     for (int b = 0; b < TJ; ++b)
; #pragma unroll
;       for (int r = 0; r < 16; ++r) acc[a][b][r] = 0.f;
;   const int fr = lane & 31, fh = (lane >> 5) * 8;
;   for (int kt = 0; kt < NKT; ++kt) {
;     __syncthreads();
; #pragma unroll
;     for (int it = 0; it < 4; ++it) {
;       *(u32x4*)(Xs + (lr + 32 * it) * LSTR + lc) = xr[it];
;       *(u32x4*)(Ys + (lr + 32 * it) * LSTR + lc) = yr[it];
;     }
;     __syncthreads();
;     if (kt + 1 < NKT) {
; #pragma unroll
;       for (int it = 0; it < 4; ++it) {
;         xr[it] = *(const u32x4*)(xg + (size_t)it * 32 * RS + (kt + 1) * 64);
;         yr[it] = *(const u32x4*)(yg + (size_t)it * 32 * RS + (kt + 1) * 64);
;       }
;     }
; DI void phase_peer_q(const Params& p, int layer, u16* lds, const int WAVE_S) {
;     ...
;   for (;;) {
;     const int slot = next_item(ctr, WAVE_S);
;     if (slot >= 512) break;
;     const int head = slot & 7, tt = (slot >> 3) * 8 + xcd;
;     float t0[16], t[16];
; #pragma unroll 1
;     for (int half = 0; half < 2; ++half) {
;       f32x16 acc[4][1];
;       gemm_tile<4, 1>(W + (size_t)(head * 2 + half) * 128 * DM, p.hb() + (size_t)tt * 128 * DM, acc, lds, 0, wave * 32, WAVE_S);
.LBB0_390:
	s_or_b32 s28, s19, s18
	v_mbcnt_lo_u32_b32 v12, -1, 0
	v_mbcnt_hi_u32_b32 v12, -1, v12
	s_xor_b64 s[46:47], s[48:49], -1
	v_add_u32_e32 v0, s33, v12
	s_lshl_b64 s[50:51], s[28:29], 1
	v_ashrrev_i32_e32 v2, 3, v0
	s_add_u32 s50, s84, s50
	v_ashrrev_i32_e32 v3, 31, v2
	s_addc_u32 s51, s85, s51
	v_lshlrev_b64 v[4:5], 11, v[2:3]
	v_lshlrev_b32_e32 v0, 4, v12
	v_lshl_add_u64 v[6:7], s[50:51], 0, v[4:5]
	v_and_b32_e32 v0, 0x70, v0
	s_mov_b32 s100, s50
	s_mov_b32 s101, s51
	v_or_b32_e32 v119, v4, v0
	v_bfe_u32 v134, v2, 1, 3
	v_lshlrev_b32_e32 v134, 4, v134
	v_xor_b32_e32 v134, v0, v134
	v_lshl_or_b32 v118, v2, 7, v134
	s_lshr_b32 vcc_lo, s33, 7
	s_lshl_b32 vcc_lo, vcc_lo, 5
	s_lshr_b32 s32, s33, 6
	s_lshl_b32 s32, s32, 12
	s_add_u32 s41, s32, 0x8000
	s_add_u32 s41, s41, vcc_lo
	s_lshr_b32 vcc_lo, s33, 1
	v_lshrrev_b32_e32 v135, 3, v12
	v_add_u32_e32 v135, vcc_lo, v135
	v_lshlrev_b32_e32 v135, 11, v135
	v_and_b32_e32 v136, 7, v12
	v_lshrrev_b32_e32 v137, 4, v12
	v_xor_b32_e32 v136, v136, v137
	v_lshl_add_u32 v120, v136, 4, v135
	v_xor_b32_e32 v136, 4, v136
	v_lshl_add_u32 v121, v136, 4, v135
	v_add_u32_e32 v121, 0x3c00, v121
	v_and_b32_e32 v138, 31, v12
	v_lshlrev_b32_e32 v138, 7, v138
	v_bfe_u32 v139, v12, 1, 3
	v_lshrrev_b32_e32 v140, 5, v12
	v_xor_b32_e32 v139, v139, v140
	v_xor_b32_e32 v141, 0, v139
	v_lshl_add_u32 v114, v141, 4, v138
	v_xor_b32_e32 v141, 2, v139
	v_lshl_add_u32 v115, v141, 4, v138
	v_xor_b32_e32 v141, 4, v139
	v_lshl_add_u32 v116, v141, 4, v138
	v_xor_b32_e32 v141, 6, v139
	v_lshl_add_u32 v117, v141, 4, v138
	v_lshl_add_u64 v[6:7], v[6:7], 0, v[0:1]
	v_lshl_add_u64 v[8:9], s[44:45], 0, v[4:5]
	s_nop 0
	v_add_co_u32_e32 v8, vcc, s81, v6
	global_load_dwordx4 v[70:73], v119, s[44:45]
	v_add_u32_e32 v133, s81, v119
	global_load_dwordx4 v[78:81], v133, s[44:45]
	v_addc_co_u32_e32 v9, vcc, 0, v7, vcc
	v_add_co_u32_e32 v10, vcc, s81, v116
	v_and_b32_e32 v3, 31, v12
	s_nop 0
	v_addc_co_u32_e32 v11, vcc, 0, v117, vcc
	v_add_u32_e32 v133, s12, v119
	global_load_dwordx4 v[86:89], v133, s[44:45]
	v_add_u32_e32 v133, s86, v119
	global_load_dwordx4 v[94:97], v133, s[44:45]
	v_add_co_u32_e32 v8, vcc, s12, v6
	s_nop 0
	s_nop 0
	v_addc_co_u32_e32 v9, vcc, 0, v7, vcc
	v_add_co_u32_e32 v10, vcc, s12, v116
	s_add_i32 s28, s18, s19
	s_nop 0
	v_addc_co_u32_e32 v11, vcc, 0, v117, vcc
	v_add_co_u32_e32 v6, vcc, s86, v6
	s_mov_b32 m0, s32
	s_nop 0
	global_load_lds_dwordx4 v120, s[100:101]
	global_load_lds_dwordx4 v121, s[100:101] offset:1024
	v_add_u32_e32 v133, 0x7800, v120
	global_load_lds_dwordx4 v133, s[100:101] offset:2048
	v_add_u32_e32 v133, 0x7800, v121
	global_load_lds_dwordx4 v133, s[100:101] offset:3072
	v_addc_co_u32_e32 v7, vcc, 0, v7, vcc
	v_add_co_u32_e32 v8, vcc, s86, v116
	v_and_b32_e32 v0, 7, v12
	s_nop 0
	v_addc_co_u32_e32 v9, vcc, 0, v117, vcc
	global_load_dwordx4 v[66:69], v119, s[44:45] offset:128
	v_add_u32_e32 v133, s81, v119
	global_load_dwordx4 v[74:77], v133, s[44:45] offset:128
	v_add_u32_e32 v133, s12, v119
	global_load_dwordx4 v[82:85], v133, s[44:45] offset:128
	v_add_u32_e32 v133, s86, v119
	global_load_dwordx4 v[90:93], v133, s[44:45] offset:128
	v_lshrrev_b32_e32 v6, 1, v12
	v_and_b32_e32 v6, 16, v6
	v_or_b32_e32 v7, v3, v122
	s_nop 0
	s_lshl_b64 s[50:51], s[28:29], 1
	s_add_u32 s50, s96, s50
	v_mul_u32_u24_e32 v3, 0x90, v3
	v_lshl_or_b32 v4, v0, 4, v4
	s_addc_u32 s51, s97, s51
	v_mov_b32_e32 v2, 0
	s_nop 0
	s_mov_b64 s[50:51], s[44:45]
	s_nop 0
	v_mov_b32_e32 v3, v2
	v_mov_b32_e32 v4, v2
	v_mov_b32_e32 v5, v2
	v_mov_b32_e32 v6, v2
	v_mov_b32_e32 v7, v2
	v_mov_b32_e32 v8, v2
	v_mov_b32_e32 v9, v2
	v_mov_b32_e32 v10, v2
	v_mov_b32_e32 v11, v2
	v_mov_b32_e32 v12, v2
	v_mov_b32_e32 v13, v2
	v_mov_b32_e32 v14, v2
	v_mov_b32_e32 v15, v2
	v_mov_b32_e32 v16, v2
	v_mov_b32_e32 v17, v2
	v_mov_b32_e32 v18, v2
	v_mov_b32_e32 v19, v2
	v_mov_b32_e32 v20, v2
	v_mov_b32_e32 v21, v2
	v_mov_b32_e32 v22, v2
	v_mov_b32_e32 v23, v2
	v_mov_b32_e32 v24, v2
	v_mov_b32_e32 v25, v2
	v_mov_b32_e32 v26, v2
	v_mov_b32_e32 v27, v2
	v_mov_b32_e32 v28, v2
	v_mov_b32_e32 v29, v2
	v_mov_b32_e32 v30, v2
	v_mov_b32_e32 v31, v2
	v_mov_b32_e32 v32, v2
	v_mov_b32_e32 v33, v2
	s_waitcnt vmcnt(12)
	v_mov_b32_e32 v34, v2
	v_mov_b32_e32 v35, v2
	v_mov_b32_e32 v36, v2
	v_mov_b32_e32 v37, v2
	s_waitcnt vmcnt(8)
	v_mov_b32_e32 v38, v2
	v_mov_b32_e32 v39, v2
	v_mov_b32_e32 v40, v2
	v_mov_b32_e32 v41, v2
	v_mov_b32_e32 v42, v2
	v_mov_b32_e32 v43, v2
	v_mov_b32_e32 v44, v2
	v_mov_b32_e32 v45, v2
	v_mov_b32_e32 v46, v2
	v_mov_b32_e32 v47, v2
	v_mov_b32_e32 v48, v2
	v_mov_b32_e32 v49, v2
	v_mov_b32_e32 v50, v2
	v_mov_b32_e32 v51, v2
	v_mov_b32_e32 v52, v2
	v_mov_b32_e32 v53, v2
	s_waitcnt vmcnt(8)
	v_mov_b32_e32 v54, v2
	v_mov_b32_e32 v55, v2
	v_mov_b32_e32 v56, v2
	v_mov_b32_e32 v57, v2
	v_mov_b32_e32 v58, v2
	v_mov_b32_e32 v59, v2
	v_mov_b32_e32 v60, v2
	v_mov_b32_e32 v61, v2
	v_mov_b32_e32 v62, v2
	v_mov_b32_e32 v63, v2
	v_mov_b32_e32 v64, v2
	v_mov_b32_e32 v65, v2
	s_movk_i32 s19, 7
; #define MFMA32(a, b, c) __builtin_amdgcn_mfma_f32_32x32x16_bf16((a), (b), (c), 0, 0, 0)
;     ...
;   for (int kt = 0; kt < NKT; ++kt) {
;     __syncthreads();
; #pragma unroll
;     for (int it = 0; it < 4; ++it) {
;       *(u32x4*)(Xs + (lr + 32 * it) * LSTR + lc) = xr[it];
;       *(u32x4*)(Ys + (lr + 32 * it) * LSTR + lc) = yr[it];
;     }
;     __syncthreads();
;     if (kt + 1 < NKT) {
; #pragma unroll
;       for (int it = 0; it < 4; ++it) {
;         xr[it] = *(const u32x4*)(xg + (size_t)it * 32 * RS + (kt + 1) * 64);
;         yr[it] = *(const u32x4*)(yg + (size_t)it * 32 * RS + (kt + 1) * 64);
;       }
;     }
; #pragma unroll
;     for (int ks = 0; ks < 4; ++ks) {
;       bf16x8 af[TI], bfr[TJ];
; #pragma unroll
;       for (int a = 0; a < TI; ++a) af[a] = *(const bf16x8*)(Xs + (wi0 + a * 32 + fr) * LSTR + ks * 16 + fh);
; #pragma unroll
;       for (int b = 0; b < TJ; ++b) bfr[b] = *(const bf16x8*)(Ys + (wj0 + b * 32 + fr) * LSTR + ks * 16 + fh);
; #pragma unroll
;       for (int a = 0; a < TI; ++a)
; #pragma unroll
;         for (int b = 0; b < TJ; ++b) acc[a][b] = MFMA32(af[a], bfr[b], acc[a][b]);
;     }
;     __builtin_amdgcn_iglp_opt(1);
;   }
.Lwd_k_pq:
	s_barrier
	s_waitcnt vmcnt(11)
	ds_write_b128 v118, v[70:73] offset:16384
	s_waitcnt vmcnt(10)
	ds_write_b128 v118, v[78:81] offset:20480
	s_waitcnt vmcnt(9)
	ds_write_b128 v118, v[86:89] offset:24576
	s_waitcnt vmcnt(8)
	ds_write_b128 v118, v[94:97] offset:28672
	s_waitcnt vmcnt(4)
	s_add_u32 s100, s100, 0x80
	s_addc_u32 s101, s101, 0
	s_mov_b32 m0, s41
	s_nop 0
	global_load_lds_dwordx4 v120, s[100:101]
	global_load_lds_dwordx4 v121, s[100:101] offset:1024
	v_add_u32_e32 v133, 0x7800, v120
	global_load_lds_dwordx4 v133, s[100:101] offset:2048
	v_add_u32_e32 v133, 0x7800, v121
	global_load_lds_dwordx4 v133, s[100:101] offset:3072
	s_waitcnt lgkmcnt(0)
	s_barrier
	ds_read_b128 v[134:137], v114 offset:4096
	ds_read_b128 v[138:141], v114 offset:8192
	ds_read_b128 v[142:145], v114 offset:12288
	ds_read_b128 v[148:151], v114
	ds_read_b128 v[152:155], v115
	v_add_u32_e32 v0, s32, v114
	ds_read_b128 v[160:163], v0 offset:16384
	v_add_u32_e32 v0, s32, v115
	ds_read_b128 v[156:159], v0 offset:16384
	s_waitcnt lgkmcnt(1)
	v_mfma_f32_32x32x16_bf16 v[34:49], v[134:137], v[160:163], v[34:49]
	ds_read_b128 v[134:137], v115 offset:4096
	v_mfma_f32_32x32x16_bf16 v[18:33], v[138:141], v[160:163], v[18:33]
	ds_read_b128 v[138:141], v115 offset:8192
	v_mfma_f32_32x32x16_bf16 v[2:17], v[142:145], v[160:163], v[2:17]
	ds_read_b128 v[142:145], v115 offset:12288
	s_waitcnt lgkmcnt(2)
	v_mfma_f32_32x32x16_bf16 v[34:49], v[134:137], v[156:159], v[34:49]
	ds_read_b128 v[134:137], v116
	s_waitcnt lgkmcnt(2)
	v_mfma_f32_32x32x16_bf16 v[18:33], v[138:141], v[156:159], v[18:33]
	ds_read_b128 v[138:141], v116 offset:4096
	s_waitcnt lgkmcnt(2)
	v_mfma_f32_32x32x16_bf16 v[2:17], v[142:145], v[156:159], v[2:17]
	ds_read_b128 v[142:145], v116 offset:8192
	v_mfma_f32_32x32x16_bf16 v[50:65], v[148:151], v[160:163], v[50:65]
	ds_read_b128 v[148:151], v116 offset:12288
	v_mfma_f32_32x32x16_bf16 v[50:65], v[152:155], v[156:159], v[50:65]
	v_add_u32_e32 v0, s32, v116
	ds_read_b128 v[152:155], v0 offset:16384
	s_waitcnt lgkmcnt(0)
	v_mfma_f32_32x32x16_bf16 v[50:65], v[134:137], v[152:155], v[50:65]
	ds_read_b128 v[134:137], v117
	v_mfma_f32_32x32x16_bf16 v[34:49], v[138:141], v[152:155], v[34:49]
	ds_read_b128 v[138:141], v117 offset:4096
	v_mfma_f32_32x32x16_bf16 v[18:33], v[142:145], v[152:155], v[18:33]
	ds_read_b128 v[142:145], v117 offset:8192
	v_mfma_f32_32x32x16_bf16 v[2:17], v[148:151], v[152:155], v[2:17]
	ds_read_b128 v[148:151], v117 offset:12288
	v_add_u32_e32 v0, s32, v117
	ds_read_b128 v[152:155], v0 offset:16384
	s_add_u32 s50, s50, 0x80
	s_addc_u32 s51, s51, 0
	global_load_dwordx4 v[70:73], v119, s[50:51] offset:128
	v_add_u32_e32 v133, s81, v119
	global_load_dwordx4 v[78:81], v133, s[50:51] offset:128
	v_add_u32_e32 v133, s12, v119
	global_load_dwordx4 v[86:89], v133, s[50:51] offset:128
	v_add_u32_e32 v133, s86, v119
	global_load_dwordx4 v[94:97], v133, s[50:51] offset:128
	s_waitcnt lgkmcnt(0)
	v_mfma_f32_32x32x16_bf16 v[50:65], v[134:137], v[152:155], v[50:65]
	v_mfma_f32_32x32x16_bf16 v[34:49], v[138:141], v[152:155], v[34:49]
	v_mfma_f32_32x32x16_bf16 v[18:33], v[142:145], v[152:155], v[18:33]
	v_mfma_f32_32x32x16_bf16 v[2:17], v[148:151], v[152:155], v[2:17]
	s_barrier
	s_waitcnt vmcnt(11)
	ds_write_b128 v118, v[66:69] offset:16384
	s_waitcnt vmcnt(10)
	ds_write_b128 v118, v[74:77] offset:20480
	s_waitcnt vmcnt(9)
	ds_write_b128 v118, v[82:85] offset:24576
	s_waitcnt vmcnt(8)
	ds_write_b128 v118, v[90:93] offset:28672
	s_waitcnt vmcnt(4)
	s_add_u32 s100, s100, 0x80
	s_addc_u32 s101, s101, 0
	s_mov_b32 m0, s32
	s_nop 0
	global_load_lds_dwordx4 v120, s[100:101]
	global_load_lds_dwordx4 v121, s[100:101] offset:1024
	v_add_u32_e32 v133, 0x7800, v120
	global_load_lds_dwordx4 v133, s[100:101] offset:2048
	v_add_u32_e32 v133, 0x7800, v121
	global_load_lds_dwordx4 v133, s[100:101] offset:3072
	s_waitcnt lgkmcnt(0)
	s_barrier
	ds_read_b128 v[134:137], v114 offset:36864
	ds_read_b128 v[138:141], v114 offset:40992
	ds_read_b128 v[142:145], v114 offset:45088
	ds_read_b128 v[148:151], v114 offset:32768
	ds_read_b128 v[152:155], v115 offset:32768
	v_add_u32_e32 v0, s32, v114
	ds_read_b128 v[160:163], v0 offset:16384
	v_add_u32_e32 v0, s32, v115
	ds_read_b128 v[156:159], v0 offset:16384
	s_waitcnt lgkmcnt(1)
	v_mfma_f32_32x32x16_bf16 v[34:49], v[134:137], v[160:163], v[34:49]
	ds_read_b128 v[134:137], v115 offset:36864
	v_mfma_f32_32x32x16_bf16 v[18:33], v[138:141], v[160:163], v[18:33]
	ds_read_b128 v[138:141], v115 offset:40992
	v_mfma_f32_32x32x16_bf16 v[2:17], v[142:145], v[160:163], v[2:17]
	ds_read_b128 v[142:145], v115 offset:45088
	s_waitcnt lgkmcnt(2)
	v_mfma_f32_32x32x16_bf16 v[34:49], v[134:137], v[156:159], v[34:49]
	ds_read_b128 v[134:137], v116 offset:32768
	s_waitcnt lgkmcnt(2)
	v_mfma_f32_32x32x16_bf16 v[18:33], v[138:141], v[156:159], v[18:33]
	ds_read_b128 v[138:141], v116 offset:36864
	s_waitcnt lgkmcnt(2)
	v_mfma_f32_32x32x16_bf16 v[2:17], v[142:145], v[156:159], v[2:17]
	ds_read_b128 v[142:145], v116 offset:40992
	v_mfma_f32_32x32x16_bf16 v[50:65], v[148:151], v[160:163], v[50:65]
	ds_read_b128 v[148:151], v116 offset:45088
	v_mfma_f32_32x32x16_bf16 v[50:65], v[152:155], v[156:159], v[50:65]
	v_add_u32_e32 v0, s32, v116
	ds_read_b128 v[152:155], v0 offset:16384
	s_waitcnt lgkmcnt(0)
	v_mfma_f32_32x32x16_bf16 v[50:65], v[134:137], v[152:155], v[50:65]
	ds_read_b128 v[134:137], v117 offset:32768
	v_mfma_f32_32x32x16_bf16 v[34:49], v[138:141], v[152:155], v[34:49]
	ds_read_b128 v[138:141], v117 offset:36864
	v_mfma_f32_32x32x16_bf16 v[18:33], v[142:145], v[152:155], v[18:33]
	ds_read_b128 v[142:145], v117 offset:40992
	v_mfma_f32_32x32x16_bf16 v[2:17], v[148:151], v[152:155], v[2:17]
	ds_read_b128 v[148:151], v117 offset:45088
	v_add_u32_e32 v0, s32, v117
	ds_read_b128 v[152:155], v0 offset:16384
	s_add_u32 s50, s50, 0x80
	s_addc_u32 s51, s51, 0
	global_load_dwordx4 v[66:69], v119, s[50:51] offset:128
	v_add_u32_e32 v133, s81, v119
	global_load_dwordx4 v[74:77], v133, s[50:51] offset:128
	v_add_u32_e32 v133, s12, v119
	global_load_dwordx4 v[82:85], v133, s[50:51] offset:128
	v_add_u32_e32 v133, s86, v119
	global_load_dwordx4 v[90:93], v133, s[50:51] offset:128
	s_waitcnt lgkmcnt(0)
	v_mfma_f32_32x32x16_bf16 v[50:65], v[134:137], v[152:155], v[50:65]
	v_mfma_f32_32x32x16_bf16 v[34:49], v[138:141], v[152:155], v[34:49]
	v_mfma_f32_32x32x16_bf16 v[18:33], v[142:145], v[152:155], v[18:33]
	v_mfma_f32_32x32x16_bf16 v[2:17], v[148:151], v[152:155], v[2:17]
	s_sub_u32 s19, s19, 1
	s_cmp_lg_u32 s19, 0
	s_cbranch_scc1 .Lwd_k_pq
; #define MFMA32(a, b, c) __builtin_amdgcn_mfma_f32_32x32x16_bf16((a), (b), (c), 0, 0, 0)
;     ...
;   for (int kt = 0; kt < NKT; ++kt) {
;     __syncthreads();
; #pragma unroll
;     for (int it = 0; it < 4; ++it) {
;       *(u32x4*)(Xs + (lr + 32 * it) * LSTR + lc) = xr[it];
;       *(u32x4*)(Ys + (lr + 32 * it) * LSTR + lc) = yr[it];
;     }
;     __syncthreads();
;     if (kt + 1 < NKT) {
; #pragma unroll
;       for (int it = 0; it < 4; ++it) {
;         xr[it] = *(const u32x4*)(xg + (size_t)it * 32 * RS + (kt + 1) * 64);
;         yr[it] = *(const u32x4*)(yg + (size_t)it * 32 * RS + (kt + 1) * 64);
;       }
;     }
; #pragma unroll
;     for (int ks = 0; ks < 4; ++ks) {
;       bf16x8 af[TI], bfr[TJ];
; #pragma unroll
;       for (int a = 0; a < TI; ++a) af[a] = *(const bf16x8*)(Xs + (wi0 + a * 32 + fr) * LSTR + ks * 16 + fh);
; #pragma unroll
;       for (int b = 0; b < TJ; ++b) bfr[b] = *(const bf16x8*)(Ys + (wj0 + b * 32 + fr) * LSTR + ks * 16 + fh);
; #pragma unroll
;       for (int a = 0; a < TI; ++a)
; #pragma unroll
;         for (int b = 0; b < TJ; ++b) acc[a][b] = MFMA32(af[a], bfr[b], acc[a][b]);
;     }
	s_barrier
	s_waitcnt vmcnt(11)
	ds_write_b128 v118, v[70:73] offset:16384
	s_waitcnt vmcnt(10)
	ds_write_b128 v118, v[78:81] offset:20480
	s_waitcnt vmcnt(9)
	ds_write_b128 v118, v[86:89] offset:24576
	s_waitcnt vmcnt(8)
	ds_write_b128 v118, v[94:97] offset:28672
	s_waitcnt vmcnt(4)
	s_add_u32 s100, s100, 0x80
	s_addc_u32 s101, s101, 0
	s_mov_b32 m0, s41
	s_nop 0
	global_load_lds_dwordx4 v120, s[100:101]
	global_load_lds_dwordx4 v121, s[100:101] offset:1024
	v_add_u32_e32 v133, 0x7800, v120
	global_load_lds_dwordx4 v133, s[100:101] offset:2048
	v_add_u32_e32 v133, 0x7800, v121
	global_load_lds_dwordx4 v133, s[100:101] offset:3072
	s_waitcnt lgkmcnt(0)
	s_barrier
	ds_read_b128 v[134:137], v114 offset:4096
	ds_read_b128 v[138:141], v114 offset:8192
	ds_read_b128 v[142:145], v114 offset:12288
	ds_read_b128 v[148:151], v114
	ds_read_b128 v[152:155], v115
	v_add_u32_e32 v0, s32, v114
	ds_read_b128 v[160:163], v0 offset:16384
	v_add_u32_e32 v0, s32, v115
	ds_read_b128 v[156:159], v0 offset:16384
	s_waitcnt lgkmcnt(1)
	v_mfma_f32_32x32x16_bf16 v[34:49], v[134:137], v[160:163], v[34:49]
	ds_read_b128 v[134:137], v115 offset:4096
	v_mfma_f32_32x32x16_bf16 v[18:33], v[138:141], v[160:163], v[18:33]
	ds_read_b128 v[138:141], v115 offset:8192
	v_mfma_f32_32x32x16_bf16 v[2:17], v[142:145], v[160:163], v[2:17]
	ds_read_b128 v[142:145], v115 offset:12288
	s_waitcnt lgkmcnt(2)
	v_mfma_f32_32x32x16_bf16 v[34:49], v[134:137], v[156:159], v[34:49]
	ds_read_b128 v[134:137], v116
	s_waitcnt lgkmcnt(2)
	v_mfma_f32_32x32x16_bf16 v[18:33], v[138:141], v[156:159], v[18:33]
	ds_read_b128 v[138:141], v116 offset:4096
	s_waitcnt lgkmcnt(2)
	v_mfma_f32_32x32x16_bf16 v[2:17], v[142:145], v[156:159], v[2:17]
	ds_read_b128 v[142:145], v116 offset:8192
	v_mfma_f32_32x32x16_bf16 v[50:65], v[148:151], v[160:163], v[50:65]
	ds_read_b128 v[148:151], v116 offset:12288
	v_mfma_f32_32x32x16_bf16 v[50:65], v[152:155], v[156:159], v[50:65]
	v_add_u32_e32 v0, s32, v116
	ds_read_b128 v[152:155], v0 offset:16384
	s_waitcnt lgkmcnt(0)
	v_mfma_f32_32x32x16_bf16 v[50:65], v[134:137], v[152:155], v[50:65]
	ds_read_b128 v[134:137], v117
	v_mfma_f32_32x32x16_bf16 v[34:49], v[138:141], v[152:155], v[34:49]
	ds_read_b128 v[138:141], v117 offset:4096
	v_mfma_f32_32x32x16_bf16 v[18:33], v[142:145], v[152:155], v[18:33]
	ds_read_b128 v[142:145], v117 offset:8192
	v_mfma_f32_32x32x16_bf16 v[2:17], v[148:151], v[152:155], v[2:17]
	ds_read_b128 v[148:151], v117 offset:12288
	v_add_u32_e32 v0, s32, v117
	ds_read_b128 v[152:155], v0 offset:16384
	s_waitcnt lgkmcnt(0)
	v_mfma_f32_32x32x16_bf16 v[50:65], v[134:137], v[152:155], v[50:65]
	v_mfma_f32_32x32x16_bf16 v[34:49], v[138:141], v[152:155], v[34:49]
	v_mfma_f32_32x32x16_bf16 v[18:33], v[142:145], v[152:155], v[18:33]
	v_mfma_f32_32x32x16_bf16 v[2:17], v[148:151], v[152:155], v[2:17]
	s_barrier
	s_waitcnt vmcnt(7)
	ds_write_b128 v118, v[66:69] offset:16384
	s_waitcnt vmcnt(6)
	ds_write_b128 v118, v[74:77] offset:20480
	s_waitcnt vmcnt(5)
	ds_write_b128 v118, v[82:85] offset:24576
	s_waitcnt vmcnt(4)
	ds_write_b128 v118, v[90:93] offset:28672
	s_waitcnt vmcnt(0)
	s_waitcnt lgkmcnt(0)
	s_barrier
	ds_read_b128 v[134:137], v114 offset:36864
	ds_read_b128 v[138:141], v114 offset:40992
	ds_read_b128 v[142:145], v114 offset:45088
	ds_read_b128 v[148:151], v114 offset:32768
	ds_read_b128 v[152:155], v115 offset:32768
	v_add_u32_e32 v0, s32, v114
	ds_read_b128 v[160:163], v0 offset:16384
	v_add_u32_e32 v0, s32, v115
	ds_read_b128 v[156:159], v0 offset:16384
	s_waitcnt lgkmcnt(1)
	v_mfma_f32_32x32x16_bf16 v[34:49], v[134:137], v[160:163], v[34:49]
	ds_read_b128 v[134:137], v115 offset:36864
	v_mfma_f32_32x32x16_bf16 v[18:33], v[138:141], v[160:163], v[18:33]
	ds_read_b128 v[138:141], v115 offset:40992
	v_mfma_f32_32x32x16_bf16 v[2:17], v[142:145], v[160:163], v[2:17]
	ds_read_b128 v[142:145], v115 offset:45088
	s_waitcnt lgkmcnt(2)
	v_mfma_f32_32x32x16_bf16 v[34:49], v[134:137], v[156:159], v[34:49]
	ds_read_b128 v[134:137], v116 offset:32768
	s_waitcnt lgkmcnt(2)
	v_mfma_f32_32x32x16_bf16 v[18:33], v[138:141], v[156:159], v[18:33]
	ds_read_b128 v[138:141], v116 offset:36864
	s_waitcnt lgkmcnt(2)
	v_mfma_f32_32x32x16_bf16 v[2:17], v[142:145], v[156:159], v[2:17]
	ds_read_b128 v[142:145], v116 offset:40992
	v_mfma_f32_32x32x16_bf16 v[50:65], v[148:151], v[160:163], v[50:65]
	ds_read_b128 v[148:151], v116 offset:45088
	v_mfma_f32_32x32x16_bf16 v[50:65], v[152:155], v[156:159], v[50:65]
	v_add_u32_e32 v0, s32, v116
	ds_read_b128 v[152:155], v0 offset:16384
	s_waitcnt lgkmcnt(0)
	v_mfma_f32_32x32x16_bf16 v[50:65], v[134:137], v[152:155], v[50:65]
	ds_read_b128 v[134:137], v117 offset:32768
	v_mfma_f32_32x32x16_bf16 v[34:49], v[138:141], v[152:155], v[34:49]
	ds_read_b128 v[138:141], v117 offset:36864
	v_mfma_f32_32x32x16_bf16 v[18:33], v[142:145], v[152:155], v[18:33]
	ds_read_b128 v[142:145], v117 offset:40992
	v_mfma_f32_32x32x16_bf16 v[2:17], v[148:151], v[152:155], v[2:17]
	ds_read_b128 v[148:151], v117 offset:45088
	v_add_u32_e32 v0, s32, v117
	ds_read_b128 v[152:155], v0 offset:16384
	s_waitcnt lgkmcnt(0)
; DI void ins16n(float (&t)[16], float x, int nf) {
; #pragma unroll
;   for (int i = 15; i >= 1; --i)
;     if (i <= nf) t[i] = __builtin_amdgcn_fmed3f(t[i - 1], t[i], x);
;   t[0] = fmaxf(t[0], x);
; }
; DI void phase_peer_q(const Params& p, int layer, u16* lds, const int WAVE_S) {
;     ...
;       for (int nt = 0; nt < 4; ++nt)
; #pragma unroll
;         for (int i = 0; i < 16; ++i) {
;           const uint32_t n = nt * 32 + (i & 3) + 8 * (i >> 2) + 4 * h;
;           const float v = __uint_as_float((__float_as_uint(acc[nt][0][i]) & ~127u) | n);
;           ins16n(t, v, nt * 16 + i);
	v_mfma_f32_32x32x16_bf16 v[50:65], v[134:137], v[152:155], v[50:65]
	v_mfma_f32_32x32x16_bf16 v[34:49], v[138:141], v[152:155], v[34:49]
	v_mfma_f32_32x32x16_bf16 v[18:33], v[142:145], v[152:155], v[18:33]
	v_mfma_f32_32x32x16_bf16 v[2:17], v[148:151], v[152:155], v[2:17]
	s_nop 7
	s_nop 7
	s_andn2_b64 vcc, exec, s[48:49]
	v_and_or_b32 v0, v50, s88, v123
	v_max_f32_e32 v0, v0, v0
	v_or_b32_e32 v50, 1, v123
	v_max_f32_e32 v0, 0xff61b1e6, v0
	v_and_or_b32 v50, v51, s88, v50
	v_med3_f32 v51, v0, v50, s92
	v_max_f32_e32 v50, v50, v50
	v_max_f32_e32 v0, v0, v50
	v_or_b32_e32 v50, 2, v123
	v_and_or_b32 v50, v52, s88, v50
	v_med3_f32 v52, v51, v50, s92
	v_med3_f32 v51, v0, v51, v50
	v_max_f32_e32 v50, v50, v50
	v_max_f32_e32 v0, v0, v50
	v_or_b32_e32 v50, 3, v123
	v_and_or_b32 v50, v53, s88, v50
	v_med3_f32 v53, v52, v50, s92
	v_med3_f32 v52, v51, v52, v50
	v_med3_f32 v51, v0, v51, v50
	v_max_f32_e32 v50, v50, v50
	v_max_f32_e32 v0, v0, v50
	v_or_b32_e32 v50, 8, v123
	v_and_or_b32 v50, v54, s88, v50
	v_med3_f32 v54, v53, v50, s92
	v_med3_f32 v53, v52, v53, v50
	v_med3_f32 v52, v51, v52, v50
	v_med3_f32 v51, v0, v51, v50
	v_max_f32_e32 v50, v50, v50
	v_max_f32_e32 v0, v0, v50
	v_or_b32_e32 v50, 9, v123
	v_and_or_b32 v50, v55, s88, v50
	v_med3_f32 v55, v54, v50, s92
	v_med3_f32 v54, v53, v54, v50
	v_med3_f32 v53, v52, v53, v50
	v_med3_f32 v52, v51, v52, v50
	v_med3_f32 v51, v0, v51, v50
	v_max_f32_e32 v50, v50, v50
	v_max_f32_e32 v0, v0, v50
	v_or_b32_e32 v50, 10, v123
	v_and_or_b32 v50, v56, s88, v50
	v_med3_f32 v56, v55, v50, s92
	v_med3_f32 v55, v54, v55, v50
	v_med3_f32 v54, v53, v54, v50
	v_med3_f32 v53, v52, v53, v50
	v_med3_f32 v52, v51, v52, v50
	v_med3_f32 v51, v0, v51, v50
	v_max_f32_e32 v50, v50, v50
	v_max_f32_e32 v0, v0, v50
	v_or_b32_e32 v50, 11, v123
	v_and_or_b32 v50, v57, s88, v50
	v_med3_f32 v57, v56, v50, s92
	v_med3_f32 v56, v55, v56, v50
	v_med3_f32 v55, v54, v55, v50
	v_med3_f32 v54, v53, v54, v50
	v_med3_f32 v53, v52, v53, v50
	v_med3_f32 v52, v51, v52, v50
	v_med3_f32 v51, v0, v51, v50
	v_max_f32_e32 v50, v50, v50
	v_max_f32_e32 v0, v0, v50
	v_or_b32_e32 v50, 16, v123
	v_and_or_b32 v50, v58, s88, v50
	v_med3_f32 v58, v57, v50, s92
	v_med3_f32 v57, v56, v57, v50
	v_med3_f32 v56, v55, v56, v50
	v_med3_f32 v55, v54, v55, v50
	v_med3_f32 v54, v53, v54, v50
	v_med3_f32 v53, v52, v53, v50
	v_med3_f32 v52, v51, v52, v50
	v_med3_f32 v51, v0, v51, v50
	v_max_f32_e32 v50, v50, v50
	v_max_f32_e32 v0, v0, v50
	v_or_b32_e32 v50, 17, v123
	v_and_or_b32 v50, v59, s88, v50
	v_med3_f32 v59, v58, v50, s92
	v_med3_f32 v58, v57, v58, v50
	v_med3_f32 v57, v56, v57, v50
	v_med3_f32 v56, v55, v56, v50
	v_med3_f32 v55, v54, v55, v50
	v_med3_f32 v54, v53, v54, v50
	v_med3_f32 v53, v52, v53, v50
	v_med3_f32 v52, v51, v52, v50
	v_med3_f32 v51, v0, v51, v50
	v_max_f32_e32 v50, v50, v50
	v_max_f32_e32 v0, v0, v50
	v_or_b32_e32 v50, 18, v123
	v_and_or_b32 v50, v60, s88, v50
	v_med3_f32 v60, v59, v50, s92
	v_med3_f32 v59, v58, v59, v50
	v_med3_f32 v58, v57, v58, v50
	v_med3_f32 v57, v56, v57, v50
	v_med3_f32 v56, v55, v56, v50
	v_med3_f32 v55, v54, v55, v50
	v_med3_f32 v54, v53, v54, v50
	v_med3_f32 v53, v52, v53, v50
	v_med3_f32 v52, v51, v52, v50
	v_med3_f32 v51, v0, v51, v50
	v_max_f32_e32 v50, v50, v50
	v_max_f32_e32 v0, v0, v50
	v_or_b32_e32 v50, 19, v123
	v_and_or_b32 v50, v61, s88, v50
	v_med3_f32 v61, v60, v50, s92
	v_med3_f32 v60, v59, v60, v50
	v_med3_f32 v59, v58, v59, v50
	v_med3_f32 v58, v57, v58, v50
	v_med3_f32 v57, v56, v57, v50
	v_med3_f32 v56, v55, v56, v50
	v_med3_f32 v55, v54, v55, v50
	v_med3_f32 v54, v53, v54, v50
	v_med3_f32 v53, v52, v53, v50
	v_med3_f32 v52, v51, v52, v50
	v_med3_f32 v51, v0, v51, v50
	v_max_f32_e32 v50, v50, v50
	v_max_f32_e32 v0, v0, v50
	v_or_b32_e32 v50, 24, v123
	v_and_or_b32 v50, v62, s88, v50
	v_med3_f32 v62, v61, v50, s92
	v_med3_f32 v61, v60, v61, v50
	v_med3_f32 v60, v59, v60, v50
	v_med3_f32 v59, v58, v59, v50
	v_med3_f32 v58, v57, v58, v50
	v_med3_f32 v57, v56, v57, v50
	v_med3_f32 v56, v55, v56, v50
	v_med3_f32 v55, v54, v55, v50
	v_med3_f32 v54, v53, v54, v50
	v_med3_f32 v53, v52, v53, v50
	v_med3_f32 v52, v51, v52, v50
	v_med3_f32 v51, v0, v51, v50
	v_max_f32_e32 v50, v50, v50
	v_max_f32_e32 v0, v0, v50
	v_or_b32_e32 v50, 25, v123
	v_and_or_b32 v50, v63, s88, v50
	v_med3_f32 v63, v62, v50, s92
	v_med3_f32 v62, v61, v62, v50
	v_med3_f32 v61, v60, v61, v50
	v_med3_f32 v60, v59, v60, v50
	v_med3_f32 v59, v58, v59, v50
	v_med3_f32 v58, v57, v58, v50
	v_med3_f32 v57, v56, v57, v50
	v_med3_f32 v56, v55, v56, v50
	v_med3_f32 v55, v54, v55, v50
	v_med3_f32 v54, v53, v54, v50
	v_med3_f32 v53, v52, v53, v50
	v_med3_f32 v52, v51, v52, v50
	v_med3_f32 v51, v0, v51, v50
	v_max_f32_e32 v50, v50, v50
	v_max_f32_e32 v0, v0, v50
	v_or_b32_e32 v50, 26, v123
	v_and_or_b32 v50, v64, s88, v50
	v_med3_f32 v64, v63, v50, s92
	v_med3_f32 v63, v62, v63, v50
	v_med3_f32 v62, v61, v62, v50
	v_med3_f32 v61, v60, v61, v50
	v_med3_f32 v60, v59, v60, v50
	v_med3_f32 v59, v58, v59, v50
	v_med3_f32 v58, v57, v58, v50
	v_med3_f32 v57, v56, v57, v50
	v_med3_f32 v56, v55, v56, v50
	v_med3_f32 v55, v54, v55, v50
	v_med3_f32 v54, v53, v54, v50
	v_med3_f32 v53, v52, v53, v50
	v_med3_f32 v52, v51, v52, v50
	v_med3_f32 v51, v0, v51, v50
	v_max_f32_e32 v50, v50, v50
	v_max_f32_e32 v0, v0, v50
	v_or_b32_e32 v50, 27, v123
	v_and_or_b32 v50, v65, s88, v50
	v_med3_f32 v65, v64, v50, s92
	v_med3_f32 v64, v63, v64, v50
	v_med3_f32 v63, v62, v63, v50
	v_med3_f32 v62, v61, v62, v50
	v_med3_f32 v61, v60, v61, v50
	v_med3_f32 v60, v59, v60, v50
	v_med3_f32 v59, v58, v59, v50
	v_med3_f32 v58, v57, v58, v50
	v_med3_f32 v57, v56, v57, v50
; DI void ins16n(float (&t)[16], float x, int nf) {
; #pragma unroll
;   for (int i = 15; i >= 1; --i)
;     if (i <= nf) t[i] = __builtin_amdgcn_fmed3f(t[i - 1], t[i], x);
;   t[0] = fmaxf(t[0], x);
; }
; DI void phase_peer_q(const Params& p, int layer, u16* lds, const int WAVE_S) {
;     ...
;       for (int nt = 0; nt < 4; ++nt)
; #pragma unroll
;         for (int i = 0; i < 16; ++i) {
;           const uint32_t n = nt * 32 + (i & 3) + 8 * (i >> 2) + 4 * h;
;           const float v = __uint_as_float((__float_as_uint(acc[nt][0][i]) & ~127u) | n);
;           ins16n(t, v, nt * 16 + i);
	v_med3_f32 v56, v55, v56, v50
	v_med3_f32 v55, v54, v55, v50
	v_med3_f32 v54, v53, v54, v50
	v_med3_f32 v53, v52, v53, v50
	v_med3_f32 v52, v51, v52, v50
	v_med3_f32 v51, v0, v51, v50
	v_max_f32_e32 v50, v50, v50
	v_max_f32_e32 v0, v0, v50
	v_or_b32_e32 v50, 32, v123
	v_and_or_b32 v34, v34, s88, v50
	v_med3_f32 v50, v64, v65, v34
	v_med3_f32 v64, v63, v64, v34
	v_med3_f32 v63, v62, v63, v34
	v_med3_f32 v62, v61, v62, v34
	v_med3_f32 v61, v60, v61, v34
	v_med3_f32 v60, v59, v60, v34
	v_med3_f32 v59, v58, v59, v34
	v_med3_f32 v58, v57, v58, v34
	v_med3_f32 v57, v56, v57, v34
	v_med3_f32 v56, v55, v56, v34
	v_med3_f32 v55, v54, v55, v34
	v_med3_f32 v54, v53, v54, v34
	v_med3_f32 v53, v52, v53, v34
	v_med3_f32 v52, v51, v52, v34
	v_med3_f32 v51, v0, v51, v34
	v_max_f32_e32 v34, v34, v34
	v_max_f32_e32 v0, v0, v34
	v_or_b32_e32 v34, 33, v123
	v_and_or_b32 v34, v35, s88, v34
	v_med3_f32 v35, v64, v50, v34
	v_med3_f32 v50, v63, v64, v34
	v_med3_f32 v63, v62, v63, v34
	v_med3_f32 v62, v61, v62, v34
	v_med3_f32 v61, v60, v61, v34
	v_med3_f32 v60, v59, v60, v34
	v_med3_f32 v59, v58, v59, v34
	v_med3_f32 v58, v57, v58, v34
	v_med3_f32 v57, v56, v57, v34
	v_med3_f32 v56, v55, v56, v34
	v_med3_f32 v55, v54, v55, v34
	v_med3_f32 v54, v53, v54, v34
	v_med3_f32 v53, v52, v53, v34
	v_med3_f32 v52, v51, v52, v34
	v_med3_f32 v51, v0, v51, v34
	v_max_f32_e32 v34, v34, v34
	v_max_f32_e32 v0, v0, v34
	v_or_b32_e32 v34, 34, v123
	v_and_or_b32 v34, v36, s88, v34
	v_med3_f32 v35, v50, v35, v34
	v_med3_f32 v36, v63, v50, v34
	v_med3_f32 v50, v62, v63, v34
	v_med3_f32 v62, v61, v62, v34
	v_med3_f32 v61, v60, v61, v34
	v_med3_f32 v60, v59, v60, v34
	v_med3_f32 v59, v58, v59, v34
	v_med3_f32 v58, v57, v58, v34
	v_med3_f32 v57, v56, v57, v34
	v_med3_f32 v56, v55, v56, v34
	v_med3_f32 v55, v54, v55, v34
	v_med3_f32 v54, v53, v54, v34
	v_med3_f32 v53, v52, v53, v34
	v_med3_f32 v52, v51, v52, v34
	v_med3_f32 v51, v0, v51, v34
	v_max_f32_e32 v34, v34, v34
	v_max_f32_e32 v0, v0, v34
	v_or_b32_e32 v34, 35, v123
	v_and_or_b32 v34, v37, s88, v34
	v_med3_f32 v35, v36, v35, v34
	v_med3_f32 v36, v50, v36, v34
	v_med3_f32 v37, v62, v50, v34
	v_med3_f32 v50, v61, v62, v34
	v_med3_f32 v61, v60, v61, v34
	v_med3_f32 v60, v59, v60, v34
	v_med3_f32 v59, v58, v59, v34
	v_med3_f32 v58, v57, v58, v34
	v_med3_f32 v57, v56, v57, v34
	v_med3_f32 v56, v55, v56, v34
	v_med3_f32 v55, v54, v55, v34
	v_med3_f32 v54, v53, v54, v34
	v_med3_f32 v53, v52, v53, v34
	v_med3_f32 v52, v51, v52, v34
	v_med3_f32 v51, v0, v51, v34
	v_max_f32_e32 v34, v34, v34
	v_max_f32_e32 v0, v0, v34
	v_or_b32_e32 v34, 40, v123
	v_and_or_b32 v34, v38, s88, v34
	v_med3_f32 v35, v36, v35, v34
	v_med3_f32 v36, v37, v36, v34
	v_med3_f32 v37, v50, v37, v34
	v_med3_f32 v38, v61, v50, v34
	v_med3_f32 v50, v60, v61, v34
	v_med3_f32 v60, v59, v60, v34
	v_med3_f32 v59, v58, v59, v34
	v_med3_f32 v58, v57, v58, v34
	v_med3_f32 v57, v56, v57, v34
	v_med3_f32 v56, v55, v56, v34
	v_med3_f32 v55, v54, v55, v34
	v_med3_f32 v54, v53, v54, v34
	v_med3_f32 v53, v52, v53, v34
	v_med3_f32 v52, v51, v52, v34
	v_med3_f32 v51, v0, v51, v34
	v_max_f32_e32 v34, v34, v34
	v_max_f32_e32 v0, v0, v34
	v_or_b32_e32 v34, 41, v123
	v_and_or_b32 v34, v39, s88, v34
	v_med3_f32 v35, v36, v35, v34
	v_med3_f32 v36, v37, v36, v34
	v_med3_f32 v37, v38, v37, v34
	v_med3_f32 v38, v50, v38, v34
	v_med3_f32 v39, v60, v50, v34
	v_med3_f32 v50, v59, v60, v34
	v_med3_f32 v59, v58, v59, v34
	v_med3_f32 v58, v57, v58, v34
	v_med3_f32 v57, v56, v57, v34
	v_med3_f32 v56, v55, v56, v34
	v_med3_f32 v55, v54, v55, v34
	v_med3_f32 v54, v53, v54, v34
	v_med3_f32 v53, v52, v53, v34
	v_med3_f32 v52, v51, v52, v34
	v_med3_f32 v51, v0, v51, v34
	v_max_f32_e32 v34, v34, v34
	v_max_f32_e32 v0, v0, v34
	v_or_b32_e32 v34, 42, v123
	v_and_or_b32 v34, v40, s88, v34
	v_med3_f32 v35, v36, v35, v34
	v_med3_f32 v36, v37, v36, v34
	v_med3_f32 v37, v38, v37, v34
	v_med3_f32 v38, v39, v38, v34
	v_med3_f32 v39, v50, v39, v34
	v_med3_f32 v40, v59, v50, v34
	v_med3_f32 v50, v58, v59, v34
	v_med3_f32 v58, v57, v58, v34
	v_med3_f32 v57, v56, v57, v34
	v_med3_f32 v56, v55, v56, v34
	v_med3_f32 v55, v54, v55, v34
	v_med3_f32 v54, v53, v54, v34
	v_med3_f32 v53, v52, v53, v34
	v_med3_f32 v52, v51, v52, v34
	v_med3_f32 v51, v0, v51, v34
	v_max_f32_e32 v34, v34, v34
	v_max_f32_e32 v0, v0, v34
	v_or_b32_e32 v34, 43, v123
	v_and_or_b32 v34, v41, s88, v34
	v_med3_f32 v35, v36, v35, v34
	v_med3_f32 v36, v37, v36, v34
	v_med3_f32 v37, v38, v37, v34
	v_med3_f32 v38, v39, v38, v34
	v_med3_f32 v39, v40, v39, v34
	v_med3_f32 v40, v50, v40, v34
	v_med3_f32 v41, v58, v50, v34
	v_med3_f32 v50, v57, v58, v34
	v_med3_f32 v57, v56, v57, v34
	v_med3_f32 v56, v55, v56, v34
	v_med3_f32 v55, v54, v55, v34
	v_med3_f32 v54, v53, v54, v34
	v_med3_f32 v53, v52, v53, v34
	v_med3_f32 v52, v51, v52, v34
	v_med3_f32 v51, v0, v51, v34
	v_max_f32_e32 v34, v34, v34
	v_max_f32_e32 v0, v0, v34
	v_or_b32_e32 v34, 48, v123
	v_and_or_b32 v34, v42, s88, v34
	v_med3_f32 v35, v36, v35, v34
	v_med3_f32 v36, v37, v36, v34
	v_med3_f32 v37, v38, v37, v34
	v_med3_f32 v38, v39, v38, v34
	v_med3_f32 v39, v40, v39, v34
	v_med3_f32 v40, v41, v40, v34
	v_med3_f32 v41, v50, v41, v34
	v_med3_f32 v42, v57, v50, v34
	v_med3_f32 v50, v56, v57, v34
	v_med3_f32 v56, v55, v56, v34
	v_med3_f32 v55, v54, v55, v34
	v_med3_f32 v54, v53, v54, v34
	v_med3_f32 v53, v52, v53, v34
	v_med3_f32 v52, v51, v52, v34
	v_med3_f32 v51, v0, v51, v34
	v_max_f32_e32 v34, v34, v34
	v_max_f32_e32 v0, v0, v34
	v_or_b32_e32 v34, 49, v123
	v_and_or_b32 v34, v43, s88, v34
	v_med3_f32 v35, v36, v35, v34
	v_med3_f32 v36, v37, v36, v34
	v_med3_f32 v37, v38, v37, v34
	v_med3_f32 v38, v39, v38, v34
; DI void ins16n(float (&t)[16], float x, int nf) {
; #pragma unroll
;   for (int i = 15; i >= 1; --i)
;     if (i <= nf) t[i] = __builtin_amdgcn_fmed3f(t[i - 1], t[i], x);
;   t[0] = fmaxf(t[0], x);
; }
; DI void phase_peer_q(const Params& p, int layer, u16* lds, const int WAVE_S) {
;     ...
;       for (int nt = 0; nt < 4; ++nt)
; #pragma unroll
;         for (int i = 0; i < 16; ++i) {
;           const uint32_t n = nt * 32 + (i & 3) + 8 * (i >> 2) + 4 * h;
;           const float v = __uint_as_float((__float_as_uint(acc[nt][0][i]) & ~127u) | n);
;           ins16n(t, v, nt * 16 + i);
	v_med3_f32 v39, v40, v39, v34
	v_med3_f32 v40, v41, v40, v34
	v_med3_f32 v41, v42, v41, v34
	v_med3_f32 v42, v50, v42, v34
	v_med3_f32 v43, v56, v50, v34
	v_med3_f32 v50, v55, v56, v34
	v_med3_f32 v55, v54, v55, v34
	v_med3_f32 v54, v53, v54, v34
	v_med3_f32 v53, v52, v53, v34
	v_med3_f32 v52, v51, v52, v34
	v_med3_f32 v51, v0, v51, v34
	v_max_f32_e32 v34, v34, v34
	v_max_f32_e32 v0, v0, v34
	v_or_b32_e32 v34, 50, v123
	v_and_or_b32 v34, v44, s88, v34
	v_med3_f32 v35, v36, v35, v34
	v_med3_f32 v36, v37, v36, v34
	v_med3_f32 v37, v38, v37, v34
	v_med3_f32 v38, v39, v38, v34
	v_med3_f32 v39, v40, v39, v34
	v_med3_f32 v40, v41, v40, v34
	v_med3_f32 v41, v42, v41, v34
	v_med3_f32 v42, v43, v42, v34
	v_med3_f32 v43, v50, v43, v34
	v_med3_f32 v44, v55, v50, v34
	v_med3_f32 v50, v54, v55, v34
	v_med3_f32 v54, v53, v54, v34
	v_med3_f32 v53, v52, v53, v34
	v_med3_f32 v52, v51, v52, v34
	v_med3_f32 v51, v0, v51, v34
	v_max_f32_e32 v34, v34, v34
	v_max_f32_e32 v0, v0, v34
	v_or_b32_e32 v34, 51, v123
	v_and_or_b32 v34, v45, s88, v34
	v_med3_f32 v35, v36, v35, v34
	v_med3_f32 v36, v37, v36, v34
	v_med3_f32 v37, v38, v37, v34
	v_med3_f32 v38, v39, v38, v34
	v_med3_f32 v39, v40, v39, v34
	v_med3_f32 v40, v41, v40, v34
	v_med3_f32 v41, v42, v41, v34
	v_med3_f32 v42, v43, v42, v34
	v_med3_f32 v43, v44, v43, v34
	v_med3_f32 v44, v50, v44, v34
	v_med3_f32 v45, v54, v50, v34
	v_med3_f32 v50, v53, v54, v34
	v_med3_f32 v53, v52, v53, v34
	v_med3_f32 v52, v51, v52, v34
	v_med3_f32 v51, v0, v51, v34
	v_max_f32_e32 v34, v34, v34
	v_max_f32_e32 v0, v0, v34
	v_or_b32_e32 v34, 56, v123
	v_and_or_b32 v34, v46, s88, v34
	v_med3_f32 v35, v36, v35, v34
	v_med3_f32 v36, v37, v36, v34
	v_med3_f32 v37, v38, v37, v34
	v_med3_f32 v38, v39, v38, v34
	v_med3_f32 v39, v40, v39, v34
	v_med3_f32 v40, v41, v40, v34
	v_med3_f32 v41, v42, v41, v34
	v_med3_f32 v42, v43, v42, v34
	v_med3_f32 v43, v44, v43, v34
	v_med3_f32 v44, v45, v44, v34
	v_med3_f32 v45, v50, v45, v34
	v_med3_f32 v46, v53, v50, v34
	v_med3_f32 v50, v52, v53, v34
	v_med3_f32 v52, v51, v52, v34
	v_med3_f32 v51, v0, v51, v34
	v_max_f32_e32 v34, v34, v34
	v_max_f32_e32 v0, v0, v34
	v_or_b32_e32 v34, 57, v123
	v_and_or_b32 v34, v47, s88, v34
	v_med3_f32 v35, v36, v35, v34
	v_med3_f32 v36, v37, v36, v34
	v_med3_f32 v37, v38, v37, v34
	v_med3_f32 v38, v39, v38, v34
	v_med3_f32 v39, v40, v39, v34
	v_med3_f32 v40, v41, v40, v34
	v_med3_f32 v41, v42, v41, v34
	v_med3_f32 v42, v43, v42, v34
	v_med3_f32 v43, v44, v43, v34
	v_med3_f32 v44, v45, v44, v34
	v_med3_f32 v45, v46, v45, v34
	v_med3_f32 v46, v50, v46, v34
	v_med3_f32 v47, v52, v50, v34
	v_med3_f32 v50, v51, v52, v34
	v_med3_f32 v51, v0, v51, v34
	v_max_f32_e32 v34, v34, v34
	v_max_f32_e32 v0, v0, v34
	v_or_b32_e32 v34, 58, v123
	v_and_or_b32 v34, v48, s88, v34
	v_med3_f32 v35, v36, v35, v34
	v_med3_f32 v36, v37, v36, v34
	v_med3_f32 v37, v38, v37, v34
	v_med3_f32 v38, v39, v38, v34
	v_med3_f32 v39, v40, v39, v34
	v_med3_f32 v40, v41, v40, v34
	v_med3_f32 v41, v42, v41, v34
	v_med3_f32 v42, v43, v42, v34
	v_med3_f32 v43, v44, v43, v34
	v_med3_f32 v44, v45, v44, v34
	v_med3_f32 v45, v46, v45, v34
	v_med3_f32 v46, v47, v46, v34
	v_med3_f32 v47, v50, v47, v34
	v_med3_f32 v48, v51, v50, v34
	v_med3_f32 v50, v0, v51, v34
	v_max_f32_e32 v34, v34, v34
	v_max_f32_e32 v0, v0, v34
	v_or_b32_e32 v34, 59, v123
	v_and_or_b32 v34, v49, s88, v34
	v_med3_f32 v35, v36, v35, v34
	v_med3_f32 v36, v37, v36, v34
	v_med3_f32 v37, v38, v37, v34
	v_med3_f32 v38, v39, v38, v34
	v_med3_f32 v39, v40, v39, v34
	v_med3_f32 v40, v41, v40, v34
	v_med3_f32 v41, v42, v41, v34
	v_med3_f32 v42, v43, v42, v34
	v_med3_f32 v43, v44, v43, v34
	v_med3_f32 v44, v45, v44, v34
	v_med3_f32 v45, v46, v45, v34
	v_med3_f32 v46, v47, v46, v34
	v_med3_f32 v47, v48, v47, v34
	v_med3_f32 v48, v50, v48, v34
	v_med3_f32 v49, v0, v50, v34
	v_max_f32_e32 v34, v34, v34
	v_max_f32_e32 v0, v0, v34
	v_or_b32_e32 v34, 64, v123
	v_and_or_b32 v18, v18, s88, v34
	v_med3_f32 v34, v36, v35, v18
	v_med3_f32 v35, v37, v36, v18
	v_med3_f32 v36, v38, v37, v18
	v_med3_f32 v37, v39, v38, v18
	v_med3_f32 v38, v40, v39, v18
	v_med3_f32 v39, v41, v40, v18
	v_med3_f32 v40, v42, v41, v18
	v_med3_f32 v41, v43, v42, v18
	v_med3_f32 v42, v44, v43, v18
	v_med3_f32 v43, v45, v44, v18
	v_med3_f32 v44, v46, v45, v18
	v_med3_f32 v45, v47, v46, v18
	v_med3_f32 v46, v48, v47, v18
	v_med3_f32 v47, v49, v48, v18
	v_med3_f32 v48, v0, v49, v18
	v_max_f32_e32 v18, v18, v18
	v_max_f32_e32 v0, v0, v18
	v_or_b32_e32 v18, 0x41, v123
	v_and_or_b32 v18, v19, s88, v18
	v_med3_f32 v19, v35, v34, v18
	v_med3_f32 v34, v36, v35, v18
	v_med3_f32 v35, v37, v36, v18
	v_med3_f32 v36, v38, v37, v18
	v_med3_f32 v37, v39, v38, v18
	v_med3_f32 v38, v40, v39, v18
	v_med3_f32 v39, v41, v40, v18
	v_med3_f32 v40, v42, v41, v18
	v_med3_f32 v41, v43, v42, v18
	v_med3_f32 v42, v44, v43, v18
	v_med3_f32 v43, v45, v44, v18
	v_med3_f32 v44, v46, v45, v18
	v_med3_f32 v45, v47, v46, v18
	v_med3_f32 v46, v48, v47, v18
	v_med3_f32 v47, v0, v48, v18
	v_max_f32_e32 v18, v18, v18
	v_max_f32_e32 v0, v0, v18
	v_or_b32_e32 v18, 0x42, v123
	v_and_or_b32 v18, v20, s88, v18
	v_med3_f32 v19, v34, v19, v18
	v_med3_f32 v20, v35, v34, v18
	v_med3_f32 v34, v36, v35, v18
	v_med3_f32 v35, v37, v36, v18
	v_med3_f32 v36, v38, v37, v18
	v_med3_f32 v37, v39, v38, v18
	v_med3_f32 v38, v40, v39, v18
	v_med3_f32 v39, v41, v40, v18
	v_med3_f32 v40, v42, v41, v18
	v_med3_f32 v41, v43, v42, v18
	v_med3_f32 v42, v44, v43, v18
	v_med3_f32 v43, v45, v44, v18
	v_med3_f32 v44, v46, v45, v18
	v_med3_f32 v45, v47, v46, v18
	v_med3_f32 v46, v0, v47, v18
	v_max_f32_e32 v18, v18, v18
	v_max_f32_e32 v0, v0, v18
; DI void ins16n(float (&t)[16], float x, int nf) {
; #pragma unroll
;   for (int i = 15; i >= 1; --i)
;     if (i <= nf) t[i] = __builtin_amdgcn_fmed3f(t[i - 1], t[i], x);
;   t[0] = fmaxf(t[0], x);
; }
; DI void phase_peer_q(const Params& p, int layer, u16* lds, const int WAVE_S) {
;     ...
;       for (int nt = 0; nt < 4; ++nt)
; #pragma unroll
;         for (int i = 0; i < 16; ++i) {
;           const uint32_t n = nt * 32 + (i & 3) + 8 * (i >> 2) + 4 * h;
;           const float v = __uint_as_float((__float_as_uint(acc[nt][0][i]) & ~127u) | n);
;           ins16n(t, v, nt * 16 + i);
	v_or_b32_e32 v18, 0x43, v123
	v_and_or_b32 v18, v21, s88, v18
	v_med3_f32 v19, v20, v19, v18
	v_med3_f32 v20, v34, v20, v18
	v_med3_f32 v21, v35, v34, v18
	v_med3_f32 v34, v36, v35, v18
	v_med3_f32 v35, v37, v36, v18
	v_med3_f32 v36, v38, v37, v18
	v_med3_f32 v37, v39, v38, v18
	v_med3_f32 v38, v40, v39, v18
	v_med3_f32 v39, v41, v40, v18
	v_med3_f32 v40, v42, v41, v18
	v_med3_f32 v41, v43, v42, v18
	v_med3_f32 v42, v44, v43, v18
	v_med3_f32 v43, v45, v44, v18
	v_med3_f32 v44, v46, v45, v18
	v_med3_f32 v45, v0, v46, v18
	v_max_f32_e32 v18, v18, v18
	v_max_f32_e32 v0, v0, v18
	v_or_b32_e32 v18, 0x48, v123
	v_and_or_b32 v18, v22, s88, v18
	v_med3_f32 v19, v20, v19, v18
	v_med3_f32 v20, v21, v20, v18
	v_med3_f32 v21, v34, v21, v18
	v_med3_f32 v22, v35, v34, v18
	v_med3_f32 v34, v36, v35, v18
	v_med3_f32 v35, v37, v36, v18
	v_med3_f32 v36, v38, v37, v18
	v_med3_f32 v37, v39, v38, v18
	v_med3_f32 v38, v40, v39, v18
	v_med3_f32 v39, v41, v40, v18
	v_med3_f32 v40, v42, v41, v18
	v_med3_f32 v41, v43, v42, v18
	v_med3_f32 v42, v44, v43, v18
	v_med3_f32 v43, v45, v44, v18
	v_med3_f32 v44, v0, v45, v18
	v_max_f32_e32 v18, v18, v18
	v_max_f32_e32 v0, v0, v18
	v_or_b32_e32 v18, 0x49, v123
	v_and_or_b32 v18, v23, s88, v18
	v_med3_f32 v19, v20, v19, v18
	v_med3_f32 v20, v21, v20, v18
	v_med3_f32 v21, v22, v21, v18
	v_med3_f32 v22, v34, v22, v18
	v_med3_f32 v23, v35, v34, v18
	v_med3_f32 v34, v36, v35, v18
	v_med3_f32 v35, v37, v36, v18
	v_med3_f32 v36, v38, v37, v18
	v_med3_f32 v37, v39, v38, v18
	v_med3_f32 v38, v40, v39, v18
	v_med3_f32 v39, v41, v40, v18
	v_med3_f32 v40, v42, v41, v18
	v_med3_f32 v41, v43, v42, v18
	v_med3_f32 v42, v44, v43, v18
	v_med3_f32 v43, v0, v44, v18
	v_max_f32_e32 v18, v18, v18
	v_max_f32_e32 v0, v0, v18
	v_or_b32_e32 v18, 0x4a, v123
	v_and_or_b32 v18, v24, s88, v18
	v_med3_f32 v19, v20, v19, v18
	v_med3_f32 v20, v21, v20, v18
	v_med3_f32 v21, v22, v21, v18
	v_med3_f32 v22, v23, v22, v18
	v_med3_f32 v23, v34, v23, v18
	v_med3_f32 v24, v35, v34, v18
	v_med3_f32 v34, v36, v35, v18
	v_med3_f32 v35, v37, v36, v18
	v_med3_f32 v36, v38, v37, v18
	v_med3_f32 v37, v39, v38, v18
	v_med3_f32 v38, v40, v39, v18
	v_med3_f32 v39, v41, v40, v18
	v_med3_f32 v40, v42, v41, v18
	v_med3_f32 v41, v43, v42, v18
	v_med3_f32 v42, v0, v43, v18
	v_max_f32_e32 v18, v18, v18
	v_max_f32_e32 v0, v0, v18
	v_or_b32_e32 v18, 0x4b, v123
	v_and_or_b32 v18, v25, s88, v18
	v_med3_f32 v19, v20, v19, v18
	v_med3_f32 v20, v21, v20, v18
	v_med3_f32 v21, v22, v21, v18
	v_med3_f32 v22, v23, v22, v18
	v_med3_f32 v23, v24, v23, v18
	v_med3_f32 v24, v34, v24, v18
	v_med3_f32 v25, v35, v34, v18
	v_med3_f32 v34, v36, v35, v18
	v_med3_f32 v35, v37, v36, v18
	v_med3_f32 v36, v38, v37, v18
	v_med3_f32 v37, v39, v38, v18
	v_med3_f32 v38, v40, v39, v18
	v_med3_f32 v39, v41, v40, v18
	v_med3_f32 v40, v42, v41, v18
	v_med3_f32 v41, v0, v42, v18
	v_max_f32_e32 v18, v18, v18
	v_max_f32_e32 v0, v0, v18
	v_or_b32_e32 v18, 0x50, v123
	v_and_or_b32 v18, v26, s88, v18
	v_med3_f32 v19, v20, v19, v18
	v_med3_f32 v20, v21, v20, v18
	v_med3_f32 v21, v22, v21, v18
	v_med3_f32 v22, v23, v22, v18
	v_med3_f32 v23, v24, v23, v18
	v_med3_f32 v24, v25, v24, v18
	v_med3_f32 v25, v34, v25, v18
	v_med3_f32 v26, v35, v34, v18
	v_med3_f32 v34, v36, v35, v18
	v_med3_f32 v35, v37, v36, v18
	v_med3_f32 v36, v38, v37, v18
	v_med3_f32 v37, v39, v38, v18
	v_med3_f32 v38, v40, v39, v18
	v_med3_f32 v39, v41, v40, v18
	v_med3_f32 v40, v0, v41, v18
	v_max_f32_e32 v18, v18, v18
	v_max_f32_e32 v0, v0, v18
	v_or_b32_e32 v18, 0x51, v123
	v_and_or_b32 v18, v27, s88, v18
	v_med3_f32 v19, v20, v19, v18
	v_med3_f32 v20, v21, v20, v18
	v_med3_f32 v21, v22, v21, v18
	v_med3_f32 v22, v23, v22, v18
	v_med3_f32 v23, v24, v23, v18
	v_med3_f32 v24, v25, v24, v18
	v_med3_f32 v25, v26, v25, v18
	v_med3_f32 v26, v34, v26, v18
	v_med3_f32 v27, v35, v34, v18
	v_med3_f32 v34, v36, v35, v18
	v_med3_f32 v35, v37, v36, v18
	v_med3_f32 v36, v38, v37, v18
	v_med3_f32 v37, v39, v38, v18
	v_med3_f32 v38, v40, v39, v18
	v_med3_f32 v39, v0, v40, v18
	v_max_f32_e32 v18, v18, v18
	v_max_f32_e32 v0, v0, v18
	v_or_b32_e32 v18, 0x52, v123
	v_and_or_b32 v18, v28, s88, v18
	v_med3_f32 v19, v20, v19, v18
	v_med3_f32 v20, v21, v20, v18
	v_med3_f32 v21, v22, v21, v18
	v_med3_f32 v22, v23, v22, v18
	v_med3_f32 v23, v24, v23, v18
	v_med3_f32 v24, v25, v24, v18
	v_med3_f32 v25, v26, v25, v18
	v_med3_f32 v26, v27, v26, v18
	v_med3_f32 v27, v34, v27, v18
	v_med3_f32 v28, v35, v34, v18
	v_med3_f32 v34, v36, v35, v18
	v_med3_f32 v35, v37, v36, v18
	v_med3_f32 v36, v38, v37, v18
	v_med3_f32 v37, v39, v38, v18
	v_med3_f32 v38, v0, v39, v18
	v_max_f32_e32 v18, v18, v18
	v_max_f32_e32 v0, v0, v18
	v_or_b32_e32 v18, 0x53, v123
	v_and_or_b32 v18, v29, s88, v18
	v_med3_f32 v19, v20, v19, v18
	v_med3_f32 v20, v21, v20, v18
	v_med3_f32 v21, v22, v21, v18
	v_med3_f32 v22, v23, v22, v18
	v_med3_f32 v23, v24, v23, v18
	v_med3_f32 v24, v25, v24, v18
	v_med3_f32 v25, v26, v25, v18
	v_med3_f32 v26, v27, v26, v18
	v_med3_f32 v27, v28, v27, v18
	v_med3_f32 v28, v34, v28, v18
	v_med3_f32 v29, v35, v34, v18
	v_med3_f32 v34, v36, v35, v18
	v_med3_f32 v35, v37, v36, v18
	v_med3_f32 v36, v38, v37, v18
	v_med3_f32 v37, v0, v38, v18
	v_max_f32_e32 v18, v18, v18
	v_max_f32_e32 v0, v0, v18
	v_or_b32_e32 v18, 0x58, v123
	v_and_or_b32 v18, v30, s88, v18
	v_med3_f32 v19, v20, v19, v18
	v_med3_f32 v20, v21, v20, v18
	v_med3_f32 v21, v22, v21, v18
	v_med3_f32 v22, v23, v22, v18
	v_med3_f32 v23, v24, v23, v18
	v_med3_f32 v24, v25, v24, v18
	v_med3_f32 v25, v26, v25, v18
	v_med3_f32 v26, v27, v26, v18
	v_med3_f32 v27, v28, v27, v18
	v_med3_f32 v28, v29, v28, v18
	v_med3_f32 v29, v34, v29, v18
; DI void ins16n(float (&t)[16], float x, int nf) {
; #pragma unroll
;   for (int i = 15; i >= 1; --i)
;     if (i <= nf) t[i] = __builtin_amdgcn_fmed3f(t[i - 1], t[i], x);
;   t[0] = fmaxf(t[0], x);
; }
; DI void phase_peer_q(const Params& p, int layer, u16* lds, const int WAVE_S) {
;     ...
;       for (int nt = 0; nt < 4; ++nt)
; #pragma unroll
;         for (int i = 0; i < 16; ++i) {
;           const uint32_t n = nt * 32 + (i & 3) + 8 * (i >> 2) + 4 * h;
;           const float v = __uint_as_float((__float_as_uint(acc[nt][0][i]) & ~127u) | n);
;           ins16n(t, v, nt * 16 + i);
	v_med3_f32 v30, v35, v34, v18
	v_med3_f32 v34, v36, v35, v18
	v_med3_f32 v35, v37, v36, v18
	v_med3_f32 v36, v0, v37, v18
	v_max_f32_e32 v18, v18, v18
	v_max_f32_e32 v0, v0, v18
	v_or_b32_e32 v18, 0x59, v123
	v_and_or_b32 v18, v31, s88, v18
	v_med3_f32 v19, v20, v19, v18
	v_med3_f32 v20, v21, v20, v18
	v_med3_f32 v21, v22, v21, v18
	v_med3_f32 v22, v23, v22, v18
	v_med3_f32 v23, v24, v23, v18
	v_med3_f32 v24, v25, v24, v18
	v_med3_f32 v25, v26, v25, v18
	v_med3_f32 v26, v27, v26, v18
	v_med3_f32 v27, v28, v27, v18
	v_med3_f32 v28, v29, v28, v18
	v_med3_f32 v29, v30, v29, v18
	v_med3_f32 v30, v34, v30, v18
	v_med3_f32 v31, v35, v34, v18
	v_med3_f32 v34, v36, v35, v18
	v_med3_f32 v35, v0, v36, v18
	v_max_f32_e32 v18, v18, v18
	v_max_f32_e32 v0, v0, v18
	v_or_b32_e32 v18, 0x5a, v123
	v_and_or_b32 v18, v32, s88, v18
	v_med3_f32 v19, v20, v19, v18
	v_med3_f32 v20, v21, v20, v18
	v_med3_f32 v21, v22, v21, v18
	v_med3_f32 v22, v23, v22, v18
	v_med3_f32 v23, v24, v23, v18
	v_med3_f32 v24, v25, v24, v18
	v_med3_f32 v25, v26, v25, v18
	v_med3_f32 v26, v27, v26, v18
	v_med3_f32 v27, v28, v27, v18
	v_med3_f32 v28, v29, v28, v18
	v_med3_f32 v29, v30, v29, v18
	v_med3_f32 v30, v31, v30, v18
	v_med3_f32 v31, v34, v31, v18
	v_med3_f32 v32, v35, v34, v18
	v_med3_f32 v34, v0, v35, v18
	v_max_f32_e32 v18, v18, v18
	v_max_f32_e32 v0, v0, v18
	v_or_b32_e32 v18, 0x5b, v123
	v_and_or_b32 v18, v33, s88, v18
	v_med3_f32 v19, v20, v19, v18
	v_med3_f32 v20, v21, v20, v18
	v_med3_f32 v21, v22, v21, v18
	v_med3_f32 v22, v23, v22, v18
	v_med3_f32 v23, v24, v23, v18
	v_med3_f32 v24, v25, v24, v18
	v_med3_f32 v25, v26, v25, v18
	v_med3_f32 v26, v27, v26, v18
	v_med3_f32 v27, v28, v27, v18
	v_med3_f32 v28, v29, v28, v18
	v_med3_f32 v29, v30, v29, v18
	v_med3_f32 v30, v31, v30, v18
	v_med3_f32 v31, v32, v31, v18
	v_med3_f32 v32, v34, v32, v18
	v_med3_f32 v33, v0, v34, v18
	v_max_f32_e32 v18, v18, v18
	v_max_f32_e32 v0, v0, v18
	v_or_b32_e32 v18, 0x60, v123
	v_and_or_b32 v2, v2, s88, v18
	v_med3_f32 v18, v20, v19, v2
	v_med3_f32 v19, v21, v20, v2
	v_med3_f32 v20, v22, v21, v2
	v_med3_f32 v21, v23, v22, v2
	v_med3_f32 v22, v24, v23, v2
	v_med3_f32 v23, v25, v24, v2
	v_med3_f32 v24, v26, v25, v2
	v_med3_f32 v25, v27, v26, v2
	v_med3_f32 v26, v28, v27, v2
	v_med3_f32 v27, v29, v28, v2
	v_med3_f32 v28, v30, v29, v2
	v_med3_f32 v29, v31, v30, v2
	v_med3_f32 v30, v32, v31, v2
	v_med3_f32 v31, v33, v32, v2
	v_med3_f32 v32, v0, v33, v2
	v_max_f32_e32 v2, v2, v2
	v_max_f32_e32 v0, v0, v2
	v_or_b32_e32 v2, 0x61, v123
	v_and_or_b32 v2, v3, s88, v2
	v_med3_f32 v3, v19, v18, v2
	v_med3_f32 v18, v20, v19, v2
	v_med3_f32 v19, v21, v20, v2
	v_med3_f32 v20, v22, v21, v2
	v_med3_f32 v21, v23, v22, v2
	v_med3_f32 v22, v24, v23, v2
	v_med3_f32 v23, v25, v24, v2
	v_med3_f32 v24, v26, v25, v2
	v_med3_f32 v25, v27, v26, v2
	v_med3_f32 v26, v28, v27, v2
	v_med3_f32 v27, v29, v28, v2
	v_med3_f32 v28, v30, v29, v2
	v_med3_f32 v29, v31, v30, v2
	v_med3_f32 v30, v32, v31, v2
	v_med3_f32 v31, v0, v32, v2
	v_max_f32_e32 v2, v2, v2
	v_max_f32_e32 v0, v0, v2
	v_or_b32_e32 v2, 0x62, v123
	v_and_or_b32 v2, v4, s88, v2
	v_med3_f32 v3, v18, v3, v2
	v_med3_f32 v4, v19, v18, v2
	v_med3_f32 v18, v20, v19, v2
	v_med3_f32 v19, v21, v20, v2
	v_med3_f32 v20, v22, v21, v2
	v_med3_f32 v21, v23, v22, v2
	v_med3_f32 v22, v24, v23, v2
	v_med3_f32 v23, v25, v24, v2
	v_med3_f32 v24, v26, v25, v2
	v_med3_f32 v25, v27, v26, v2
	v_med3_f32 v26, v28, v27, v2
	v_med3_f32 v27, v29, v28, v2
	v_med3_f32 v28, v30, v29, v2
	v_med3_f32 v29, v31, v30, v2
	v_med3_f32 v30, v0, v31, v2
	v_max_f32_e32 v2, v2, v2
	v_max_f32_e32 v0, v0, v2
	v_or_b32_e32 v2, 0x63, v123
	v_and_or_b32 v2, v5, s88, v2
	v_med3_f32 v3, v4, v3, v2
	v_med3_f32 v4, v18, v4, v2
	v_med3_f32 v5, v19, v18, v2
	v_med3_f32 v18, v20, v19, v2
	v_med3_f32 v19, v21, v20, v2
	v_med3_f32 v20, v22, v21, v2
	v_med3_f32 v21, v23, v22, v2
	v_med3_f32 v22, v24, v23, v2
	v_med3_f32 v23, v25, v24, v2
	v_med3_f32 v24, v26, v25, v2
	v_med3_f32 v25, v27, v26, v2
	v_med3_f32 v26, v28, v27, v2
	v_med3_f32 v27, v29, v28, v2
	v_med3_f32 v28, v30, v29, v2
	v_med3_f32 v29, v0, v30, v2
	v_max_f32_e32 v2, v2, v2
	v_max_f32_e32 v0, v0, v2
	v_or_b32_e32 v2, 0x68, v123
	v_and_or_b32 v2, v6, s88, v2
	v_med3_f32 v3, v4, v3, v2
	v_med3_f32 v4, v5, v4, v2
	v_med3_f32 v5, v18, v5, v2
	v_med3_f32 v6, v19, v18, v2
	v_med3_f32 v18, v20, v19, v2
	v_med3_f32 v19, v21, v20, v2
	v_med3_f32 v20, v22, v21, v2
	v_med3_f32 v21, v23, v22, v2
	v_med3_f32 v22, v24, v23, v2
	v_med3_f32 v23, v25, v24, v2
	v_med3_f32 v24, v26, v25, v2
	v_med3_f32 v25, v27, v26, v2
	v_med3_f32 v26, v28, v27, v2
	v_med3_f32 v27, v29, v28, v2
	v_med3_f32 v28, v0, v29, v2
	v_max_f32_e32 v2, v2, v2
	v_max_f32_e32 v0, v0, v2
	v_or_b32_e32 v2, 0x69, v123
	v_and_or_b32 v2, v7, s88, v2
	v_med3_f32 v3, v4, v3, v2
	v_med3_f32 v4, v5, v4, v2
	v_med3_f32 v5, v6, v5, v2
	v_med3_f32 v6, v18, v6, v2
	v_med3_f32 v7, v19, v18, v2
	v_med3_f32 v18, v20, v19, v2
	v_med3_f32 v19, v21, v20, v2
	v_med3_f32 v20, v22, v21, v2
	v_med3_f32 v21, v23, v22, v2
	v_med3_f32 v22, v24, v23, v2
	v_med3_f32 v23, v25, v24, v2
	v_med3_f32 v24, v26, v25, v2
	v_med3_f32 v25, v27, v26, v2
	v_med3_f32 v26, v28, v27, v2
	v_med3_f32 v27, v0, v28, v2
	v_max_f32_e32 v2, v2, v2
	v_max_f32_e32 v0, v0, v2
	v_or_b32_e32 v2, 0x6a, v123
	v_and_or_b32 v2, v8, s88, v2
	v_med3_f32 v3, v4, v3, v2
	v_med3_f32 v4, v5, v4, v2
	v_med3_f32 v5, v6, v5, v2
	v_med3_f32 v6, v7, v6, v2
	v_med3_f32 v7, v18, v7, v2
	v_med3_f32 v8, v19, v18, v2
	v_med3_f32 v18, v20, v19, v2
	v_med3_f32 v19, v21, v20, v2
	v_med3_f32 v20, v22, v21, v2
	v_med3_f32 v21, v23, v22, v2
	v_med3_f32 v22, v24, v23, v2
; DI void ins16n(float (&t)[16], float x, int nf) {
; #pragma unroll
;   for (int i = 15; i >= 1; --i)
;     if (i <= nf) t[i] = __builtin_amdgcn_fmed3f(t[i - 1], t[i], x);
;   t[0] = fmaxf(t[0], x);
; }
; DI void phase_peer_q(const Params& p, int layer, u16* lds, const int WAVE_S) {
;     ...
;       for (int nt = 0; nt < 4; ++nt)
; #pragma unroll
;         for (int i = 0; i < 16; ++i) {
;           const uint32_t n = nt * 32 + (i & 3) + 8 * (i >> 2) + 4 * h;
;           const float v = __uint_as_float((__float_as_uint(acc[nt][0][i]) & ~127u) | n);
;           ins16n(t, v, nt * 16 + i);
;         }
;       float o16[16];
; #pragma unroll
;       for (int i = 0; i < 16; ++i) {
;         auto rr = __builtin_amdgcn_permlane32_swap(__float_as_uint(t[i]), __float_as_uint(t[i]), false, false);
;         o16[i] = __uint_as_float(h ? rr[0] : rr[1]);
;       }
	v_med3_f32 v23, v25, v24, v2
	v_med3_f32 v24, v26, v25, v2
	v_med3_f32 v25, v27, v26, v2
	v_med3_f32 v26, v0, v27, v2
	v_max_f32_e32 v2, v2, v2
	v_max_f32_e32 v0, v0, v2
	v_or_b32_e32 v2, 0x6b, v123
	v_and_or_b32 v2, v9, s88, v2
	v_med3_f32 v3, v4, v3, v2
	v_med3_f32 v4, v5, v4, v2
	v_med3_f32 v5, v6, v5, v2
	v_med3_f32 v6, v7, v6, v2
	v_med3_f32 v7, v8, v7, v2
	v_med3_f32 v8, v18, v8, v2
	v_med3_f32 v9, v19, v18, v2
	v_med3_f32 v18, v20, v19, v2
	v_med3_f32 v19, v21, v20, v2
	v_med3_f32 v20, v22, v21, v2
	v_med3_f32 v21, v23, v22, v2
	v_med3_f32 v22, v24, v23, v2
	v_med3_f32 v23, v25, v24, v2
	v_med3_f32 v24, v26, v25, v2
	v_med3_f32 v25, v0, v26, v2
	v_max_f32_e32 v2, v2, v2
	v_max_f32_e32 v0, v0, v2
	v_and_or_b32 v2, v10, s88, v125
	v_med3_f32 v3, v4, v3, v2
	v_med3_f32 v4, v5, v4, v2
	v_med3_f32 v5, v6, v5, v2
	v_med3_f32 v6, v7, v6, v2
	v_med3_f32 v7, v8, v7, v2
	v_med3_f32 v8, v9, v8, v2
	v_med3_f32 v9, v18, v9, v2
	v_med3_f32 v10, v19, v18, v2
	v_med3_f32 v18, v20, v19, v2
	v_med3_f32 v19, v21, v20, v2
	v_med3_f32 v20, v22, v21, v2
	v_med3_f32 v21, v23, v22, v2
	v_med3_f32 v22, v24, v23, v2
	v_med3_f32 v23, v25, v24, v2
	v_med3_f32 v24, v0, v25, v2
	v_max_f32_e32 v2, v2, v2
	v_max_f32_e32 v0, v0, v2
	v_and_or_b32 v2, v11, s88, v126
	v_med3_f32 v3, v4, v3, v2
	v_med3_f32 v4, v5, v4, v2
	v_med3_f32 v5, v6, v5, v2
	v_med3_f32 v6, v7, v6, v2
	v_med3_f32 v7, v8, v7, v2
	v_med3_f32 v8, v9, v8, v2
	v_med3_f32 v9, v10, v9, v2
	v_med3_f32 v10, v18, v10, v2
	v_med3_f32 v11, v19, v18, v2
	v_med3_f32 v18, v20, v19, v2
	v_med3_f32 v19, v21, v20, v2
	v_med3_f32 v20, v22, v21, v2
	v_med3_f32 v21, v23, v22, v2
	v_med3_f32 v22, v24, v23, v2
	v_med3_f32 v23, v0, v24, v2
	v_max_f32_e32 v2, v2, v2
	v_max_f32_e32 v0, v0, v2
	v_and_or_b32 v2, v12, s88, v127
	v_med3_f32 v3, v4, v3, v2
	v_med3_f32 v4, v5, v4, v2
	v_med3_f32 v5, v6, v5, v2
	v_med3_f32 v6, v7, v6, v2
	v_med3_f32 v7, v8, v7, v2
	v_med3_f32 v8, v9, v8, v2
	v_med3_f32 v9, v10, v9, v2
	v_med3_f32 v10, v11, v10, v2
	v_med3_f32 v11, v18, v11, v2
	v_med3_f32 v12, v19, v18, v2
	v_med3_f32 v18, v20, v19, v2
	v_med3_f32 v19, v21, v20, v2
	v_med3_f32 v20, v22, v21, v2
	v_med3_f32 v21, v23, v22, v2
	v_med3_f32 v22, v0, v23, v2
	v_max_f32_e32 v2, v2, v2
	v_max_f32_e32 v0, v0, v2
	v_and_or_b32 v2, v13, s88, v128
	v_med3_f32 v3, v4, v3, v2
	v_med3_f32 v4, v5, v4, v2
	v_med3_f32 v5, v6, v5, v2
	v_med3_f32 v6, v7, v6, v2
	v_med3_f32 v7, v8, v7, v2
	v_med3_f32 v8, v9, v8, v2
	v_med3_f32 v9, v10, v9, v2
	v_med3_f32 v10, v11, v10, v2
	v_med3_f32 v11, v12, v11, v2
	v_med3_f32 v12, v18, v12, v2
	v_med3_f32 v13, v19, v18, v2
	v_med3_f32 v18, v20, v19, v2
	v_med3_f32 v19, v21, v20, v2
	v_med3_f32 v20, v22, v21, v2
	v_med3_f32 v21, v0, v22, v2
	v_max_f32_e32 v2, v2, v2
	v_max_f32_e32 v0, v0, v2
	v_and_or_b32 v2, v14, s88, v129
	v_med3_f32 v3, v4, v3, v2
	v_med3_f32 v4, v5, v4, v2
	v_med3_f32 v5, v6, v5, v2
	v_med3_f32 v6, v7, v6, v2
	v_med3_f32 v7, v8, v7, v2
	v_med3_f32 v8, v9, v8, v2
	v_med3_f32 v9, v10, v9, v2
	v_med3_f32 v10, v11, v10, v2
	v_med3_f32 v11, v12, v11, v2
	v_med3_f32 v12, v13, v12, v2
	v_med3_f32 v13, v18, v13, v2
	v_med3_f32 v14, v19, v18, v2
	v_med3_f32 v18, v20, v19, v2
	v_med3_f32 v19, v21, v20, v2
	v_med3_f32 v20, v0, v21, v2
	v_max_f32_e32 v2, v2, v2
	v_max_f32_e32 v0, v0, v2
	v_and_or_b32 v2, v15, s88, v130
	v_med3_f32 v3, v4, v3, v2
	v_med3_f32 v4, v5, v4, v2
	v_med3_f32 v5, v6, v5, v2
	v_med3_f32 v6, v7, v6, v2
	v_med3_f32 v7, v8, v7, v2
	v_med3_f32 v8, v9, v8, v2
	v_med3_f32 v9, v10, v9, v2
	v_med3_f32 v10, v11, v10, v2
	v_med3_f32 v11, v12, v11, v2
	v_med3_f32 v12, v13, v12, v2
	v_med3_f32 v13, v14, v13, v2
	v_med3_f32 v14, v18, v14, v2
	v_med3_f32 v15, v19, v18, v2
	v_med3_f32 v18, v20, v19, v2
	v_med3_f32 v19, v0, v20, v2
	v_max_f32_e32 v2, v2, v2
	v_max_f32_e32 v0, v0, v2
	v_and_or_b32 v2, v16, s88, v131
	v_med3_f32 v3, v4, v3, v2
	v_med3_f32 v4, v5, v4, v2
	v_med3_f32 v5, v6, v5, v2
	v_med3_f32 v6, v7, v6, v2
	v_med3_f32 v7, v8, v7, v2
	v_med3_f32 v8, v9, v8, v2
	v_med3_f32 v9, v10, v9, v2
	v_med3_f32 v10, v11, v10, v2
	v_med3_f32 v11, v12, v11, v2
	v_med3_f32 v12, v13, v12, v2
	v_med3_f32 v13, v14, v13, v2
	v_med3_f32 v14, v15, v14, v2
	v_med3_f32 v15, v18, v15, v2
	v_med3_f32 v16, v19, v18, v2
	v_med3_f32 v18, v0, v19, v2
	v_max_f32_e32 v2, v2, v2
	v_max_f32_e32 v0, v0, v2
	v_and_or_b32 v2, v17, s88, v132
	v_med3_f32 v3, v4, v3, v2
	v_med3_f32 v4, v5, v4, v2
	v_med3_f32 v5, v6, v5, v2
	v_med3_f32 v6, v7, v6, v2
	v_med3_f32 v7, v8, v7, v2
	v_med3_f32 v8, v9, v8, v2
	v_med3_f32 v9, v10, v9, v2
	v_med3_f32 v10, v11, v10, v2
	v_med3_f32 v11, v12, v11, v2
	v_med3_f32 v12, v13, v12, v2
	v_med3_f32 v13, v14, v13, v2
	v_med3_f32 v14, v15, v14, v2
	v_med3_f32 v15, v16, v15, v2
	v_med3_f32 v16, v18, v16, v2
	v_med3_f32 v17, v0, v18, v2
	v_max_f32_e32 v2, v2, v2
	v_max_f32_e32 v0, v0, v2
	v_mov_b32_e32 v2, v0
	v_mov_b32_e32 v18, v0
	s_nop 1
	v_permlane32_swap_b32_e32 v2, v18
	v_cndmask_b32_e64 v2, v2, v18, s[34:35]
	v_mov_b32_e32 v18, v17
	v_mov_b32_e32 v19, v17
	s_nop 1
	v_permlane32_swap_b32_e32 v18, v19
	v_cndmask_b32_e64 v18, v18, v19, s[34:35]
	v_mov_b32_e32 v19, v16
	v_mov_b32_e32 v20, v16
	s_nop 1
	v_permlane32_swap_b32_e32 v19, v20
	v_cndmask_b32_e64 v19, v19, v20, s[34:35]
	v_mov_b32_e32 v20, v15
	v_mov_b32_e32 v21, v15
	s_nop 1
	v_permlane32_swap_b32_e32 v20, v21
	v_cndmask_b32_e64 v20, v20, v21, s[34:35]
	v_mov_b32_e32 v21, v14
	v_mov_b32_e32 v22, v14
	s_nop 1
	v_permlane32_swap_b32_e32 v21, v22
	v_cndmask_b32_e64 v21, v21, v22, s[34:35]
	v_mov_b32_e32 v22, v13
	v_mov_b32_e32 v23, v13
	s_nop 1
	v_permlane32_swap_b32_e32 v22, v23
	v_cndmask_b32_e64 v22, v22, v23, s[34:35]
; DI void ins16(float (&t)[16], float x) {
; #pragma unroll
;   for (int i = 15; i >= 1; --i) t[i] = __builtin_amdgcn_fmed3f(t[i - 1], t[i], x);
;   t[0] = fmaxf(t[0], x);
; }
; DI void phase_peer_q(const Params& p, int layer, u16* lds, const int WAVE_S) {
;     ...
; #pragma unroll
;       for (int i = 0; i < 16; ++i) {
;         auto rr = __builtin_amdgcn_permlane32_swap(__float_as_uint(t[i]), __float_as_uint(t[i]), false, false);
;         o16[i] = __uint_as_float(h ? rr[0] : rr[1]);
;       }
; #pragma unroll
;       for (int i = 0; i < 16; ++i) ins16(t, o16[i]);
	v_mov_b32_e32 v23, v12
	v_mov_b32_e32 v24, v12
	s_nop 1
	v_permlane32_swap_b32_e32 v23, v24
	v_cndmask_b32_e64 v23, v23, v24, s[34:35]
	v_mov_b32_e32 v24, v11
	v_mov_b32_e32 v25, v11
	s_nop 1
	v_permlane32_swap_b32_e32 v24, v25
	v_cndmask_b32_e64 v24, v24, v25, s[34:35]
	v_mov_b32_e32 v25, v10
	v_mov_b32_e32 v26, v10
	s_nop 1
	v_permlane32_swap_b32_e32 v25, v26
	v_cndmask_b32_e64 v25, v25, v26, s[34:35]
	v_mov_b32_e32 v26, v9
	v_mov_b32_e32 v27, v9
	s_nop 1
	v_permlane32_swap_b32_e32 v26, v27
	v_cndmask_b32_e64 v26, v26, v27, s[34:35]
	v_mov_b32_e32 v27, v8
	v_mov_b32_e32 v28, v8
	s_nop 1
	v_permlane32_swap_b32_e32 v27, v28
	v_cndmask_b32_e64 v27, v27, v28, s[34:35]
	v_mov_b32_e32 v28, v7
	v_mov_b32_e32 v29, v7
	s_nop 1
	v_permlane32_swap_b32_e32 v28, v29
	v_cndmask_b32_e64 v28, v28, v29, s[34:35]
	v_mov_b32_e32 v29, v6
	v_mov_b32_e32 v30, v6
	s_nop 1
	v_permlane32_swap_b32_e32 v29, v30
	v_cndmask_b32_e64 v29, v29, v30, s[34:35]
	v_mov_b32_e32 v30, v5
	v_mov_b32_e32 v31, v5
	s_nop 1
	v_permlane32_swap_b32_e32 v30, v31
	v_cndmask_b32_e64 v30, v30, v31, s[34:35]
	v_mov_b32_e32 v31, v4
	v_mov_b32_e32 v32, v4
	s_nop 1
	v_permlane32_swap_b32_e32 v31, v32
	v_cndmask_b32_e64 v31, v31, v32, s[34:35]
	v_mov_b32_e32 v32, v3
	v_mov_b32_e32 v33, v3
	v_med3_f32 v3, v4, v3, v2
	v_med3_f32 v4, v5, v4, v2
	v_med3_f32 v5, v6, v5, v2
	v_med3_f32 v6, v7, v6, v2
	v_med3_f32 v7, v8, v7, v2
	v_med3_f32 v8, v9, v8, v2
	v_med3_f32 v9, v10, v9, v2
	v_med3_f32 v10, v11, v10, v2
	v_med3_f32 v11, v12, v11, v2
	v_med3_f32 v12, v13, v12, v2
	v_med3_f32 v13, v14, v13, v2
	v_med3_f32 v14, v15, v14, v2
	v_med3_f32 v15, v16, v15, v2
	v_med3_f32 v16, v17, v16, v2
	v_med3_f32 v17, v0, v17, v2
	v_max_f32_e32 v2, v2, v2
	v_max_f32_e32 v0, v0, v2
	v_med3_f32 v2, v4, v3, v18
	v_med3_f32 v3, v5, v4, v18
	v_med3_f32 v4, v6, v5, v18
	v_med3_f32 v5, v7, v6, v18
	v_med3_f32 v6, v8, v7, v18
	v_med3_f32 v7, v9, v8, v18
	v_med3_f32 v8, v10, v9, v18
	v_med3_f32 v9, v11, v10, v18
	v_med3_f32 v10, v12, v11, v18
	v_med3_f32 v11, v13, v12, v18
	v_med3_f32 v12, v14, v13, v18
	v_med3_f32 v13, v15, v14, v18
	v_med3_f32 v14, v16, v15, v18
	v_med3_f32 v15, v17, v16, v18
	v_med3_f32 v16, v0, v17, v18
	v_max_f32_e32 v17, v18, v18
	v_max_f32_e32 v0, v0, v17
	v_max_f32_e32 v17, v19, v19
	v_med3_f32 v2, v3, v2, v19
	v_med3_f32 v3, v4, v3, v19
	v_med3_f32 v4, v5, v4, v19
	v_med3_f32 v5, v6, v5, v19
	v_med3_f32 v6, v7, v6, v19
	v_med3_f32 v7, v8, v7, v19
	v_med3_f32 v8, v9, v8, v19
	v_med3_f32 v9, v10, v9, v19
	v_med3_f32 v10, v11, v10, v19
	v_med3_f32 v11, v12, v11, v19
	v_med3_f32 v12, v13, v12, v19
	v_med3_f32 v13, v14, v13, v19
	v_med3_f32 v14, v15, v14, v19
	v_med3_f32 v15, v16, v15, v19
	v_med3_f32 v16, v0, v16, v19
	v_max_f32_e32 v0, v0, v17
	v_max_f32_e32 v17, v20, v20
	v_med3_f32 v2, v3, v2, v20
	v_med3_f32 v3, v4, v3, v20
	v_med3_f32 v4, v5, v4, v20
	v_med3_f32 v5, v6, v5, v20
	v_med3_f32 v6, v7, v6, v20
	v_med3_f32 v7, v8, v7, v20
	v_med3_f32 v8, v9, v8, v20
	v_med3_f32 v9, v10, v9, v20
	v_med3_f32 v10, v11, v10, v20
	v_med3_f32 v11, v12, v11, v20
	v_med3_f32 v12, v13, v12, v20
	v_med3_f32 v13, v14, v13, v20
	v_med3_f32 v14, v15, v14, v20
	v_med3_f32 v15, v16, v15, v20
	v_med3_f32 v16, v0, v16, v20
	v_max_f32_e32 v0, v0, v17
	v_max_f32_e32 v17, v21, v21
	v_med3_f32 v2, v3, v2, v21
	v_med3_f32 v3, v4, v3, v21
	v_med3_f32 v4, v5, v4, v21
	v_med3_f32 v5, v6, v5, v21
	v_med3_f32 v6, v7, v6, v21
	v_med3_f32 v7, v8, v7, v21
	v_med3_f32 v8, v9, v8, v21
	v_med3_f32 v9, v10, v9, v21
	v_med3_f32 v10, v11, v10, v21
	v_med3_f32 v11, v12, v11, v21
	v_med3_f32 v12, v13, v12, v21
	v_med3_f32 v13, v14, v13, v21
	v_med3_f32 v14, v15, v14, v21
	v_med3_f32 v15, v16, v15, v21
	v_med3_f32 v16, v0, v16, v21
	v_max_f32_e32 v0, v0, v17
	v_max_f32_e32 v17, v22, v22
	v_med3_f32 v2, v3, v2, v22
	v_med3_f32 v3, v4, v3, v22
	v_med3_f32 v4, v5, v4, v22
	v_med3_f32 v5, v6, v5, v22
	v_med3_f32 v6, v7, v6, v22
	v_med3_f32 v7, v8, v7, v22
	v_med3_f32 v8, v9, v8, v22
	v_med3_f32 v9, v10, v9, v22
	v_med3_f32 v10, v11, v10, v22
	v_med3_f32 v11, v12, v11, v22
	v_med3_f32 v12, v13, v12, v22
	v_med3_f32 v13, v14, v13, v22
	v_med3_f32 v14, v15, v14, v22
	v_med3_f32 v15, v16, v15, v22
	v_med3_f32 v16, v0, v16, v22
	v_max_f32_e32 v0, v0, v17
	v_max_f32_e32 v17, v23, v23
	v_med3_f32 v2, v3, v2, v23
	v_med3_f32 v3, v4, v3, v23
	v_med3_f32 v4, v5, v4, v23
	v_med3_f32 v5, v6, v5, v23
	v_med3_f32 v6, v7, v6, v23
	v_med3_f32 v7, v8, v7, v23
	v_med3_f32 v8, v9, v8, v23
	v_med3_f32 v9, v10, v9, v23
	v_med3_f32 v10, v11, v10, v23
	v_med3_f32 v11, v12, v11, v23
	v_med3_f32 v12, v13, v12, v23
	v_med3_f32 v13, v14, v13, v23
	v_med3_f32 v14, v15, v14, v23
	v_med3_f32 v15, v16, v15, v23
	v_med3_f32 v16, v0, v16, v23
	v_max_f32_e32 v0, v0, v17
	v_max_f32_e32 v17, v24, v24
	v_med3_f32 v2, v3, v2, v24
	v_med3_f32 v3, v4, v3, v24
; DI void ins16(float (&t)[16], float x) {
; #pragma unroll
;   for (int i = 15; i >= 1; --i) t[i] = __builtin_amdgcn_fmed3f(t[i - 1], t[i], x);
;   t[0] = fmaxf(t[0], x);
; }
; DI void phase_peer_q(const Params& p, int layer, u16* lds, const int WAVE_S) {
;     ...
; #pragma unroll
;       for (int i = 0; i < 16; ++i) ins16(t, o16[i]);
;       if (half == 0) {
; #pragma unroll
;         for (int i = 0; i < 16; ++i) t0[i] = t[i];
	v_med3_f32 v4, v5, v4, v24
	v_med3_f32 v5, v6, v5, v24
	v_med3_f32 v6, v7, v6, v24
	v_med3_f32 v7, v8, v7, v24
	v_med3_f32 v8, v9, v8, v24
	v_med3_f32 v9, v10, v9, v24
	v_med3_f32 v10, v11, v10, v24
	v_med3_f32 v11, v12, v11, v24
	v_med3_f32 v12, v13, v12, v24
	v_med3_f32 v13, v14, v13, v24
	v_med3_f32 v14, v15, v14, v24
	v_med3_f32 v15, v16, v15, v24
	v_med3_f32 v16, v0, v16, v24
	v_max_f32_e32 v0, v0, v17
	v_med3_f32 v2, v3, v2, v25
	v_med3_f32 v3, v4, v3, v25
	v_med3_f32 v4, v5, v4, v25
	v_med3_f32 v5, v6, v5, v25
	v_med3_f32 v6, v7, v6, v25
	v_med3_f32 v7, v8, v7, v25
	v_med3_f32 v8, v9, v8, v25
	v_med3_f32 v9, v10, v9, v25
	v_med3_f32 v10, v11, v10, v25
	v_med3_f32 v11, v12, v11, v25
	v_med3_f32 v12, v13, v12, v25
	v_med3_f32 v13, v14, v13, v25
	v_med3_f32 v14, v15, v14, v25
	v_med3_f32 v15, v16, v15, v25
	v_med3_f32 v16, v0, v16, v25
	v_max_f32_e32 v17, v25, v25
	v_max_f32_e32 v0, v0, v17
	v_med3_f32 v2, v3, v2, v26
	v_med3_f32 v3, v4, v3, v26
	v_med3_f32 v4, v5, v4, v26
	v_med3_f32 v5, v6, v5, v26
	v_med3_f32 v6, v7, v6, v26
	v_med3_f32 v7, v8, v7, v26
	v_med3_f32 v8, v9, v8, v26
	v_med3_f32 v9, v10, v9, v26
	v_med3_f32 v10, v11, v10, v26
	v_med3_f32 v11, v12, v11, v26
	v_med3_f32 v12, v13, v12, v26
	v_med3_f32 v13, v14, v13, v26
	v_med3_f32 v14, v15, v14, v26
	v_med3_f32 v15, v16, v15, v26
	v_max_f32_e32 v17, v26, v26
	v_med3_f32 v16, v0, v16, v26
	v_max_f32_e32 v0, v0, v17
	v_med3_f32 v2, v3, v2, v27
	v_med3_f32 v3, v4, v3, v27
	v_med3_f32 v4, v5, v4, v27
	v_med3_f32 v5, v6, v5, v27
	v_med3_f32 v6, v7, v6, v27
	v_med3_f32 v7, v8, v7, v27
	v_med3_f32 v8, v9, v8, v27
	v_med3_f32 v9, v10, v9, v27
	v_med3_f32 v10, v11, v10, v27
	v_med3_f32 v11, v12, v11, v27
	v_med3_f32 v12, v13, v12, v27
	v_med3_f32 v13, v14, v13, v27
	v_med3_f32 v14, v15, v14, v27
	v_max_f32_e32 v17, v27, v27
	v_med3_f32 v15, v16, v15, v27
	v_med3_f32 v16, v0, v16, v27
	v_max_f32_e32 v0, v0, v17
	v_med3_f32 v2, v3, v2, v28
	v_med3_f32 v3, v4, v3, v28
	v_med3_f32 v4, v5, v4, v28
	v_med3_f32 v5, v6, v5, v28
	v_med3_f32 v6, v7, v6, v28
	v_med3_f32 v7, v8, v7, v28
	v_med3_f32 v8, v9, v8, v28
	v_med3_f32 v9, v10, v9, v28
	v_med3_f32 v10, v11, v10, v28
	v_med3_f32 v11, v12, v11, v28
	v_med3_f32 v12, v13, v12, v28
	v_med3_f32 v13, v14, v13, v28
	v_max_f32_e32 v17, v28, v28
	v_med3_f32 v14, v15, v14, v28
	v_med3_f32 v15, v16, v15, v28
	v_med3_f32 v16, v0, v16, v28
	v_max_f32_e32 v0, v0, v17
	v_med3_f32 v2, v3, v2, v29
	v_med3_f32 v3, v4, v3, v29
	v_med3_f32 v4, v5, v4, v29
	v_med3_f32 v5, v6, v5, v29
	v_med3_f32 v6, v7, v6, v29
	v_med3_f32 v7, v8, v7, v29
	v_med3_f32 v8, v9, v8, v29
	v_med3_f32 v9, v10, v9, v29
	v_med3_f32 v10, v11, v10, v29
	v_med3_f32 v11, v12, v11, v29
	v_med3_f32 v12, v13, v12, v29
	v_max_f32_e32 v17, v29, v29
	v_permlane32_swap_b32_e32 v32, v33
	v_med3_f32 v13, v14, v13, v29
	v_med3_f32 v14, v15, v14, v29
	v_med3_f32 v15, v16, v15, v29
	v_med3_f32 v16, v0, v16, v29
	v_max_f32_e32 v0, v0, v17
	v_med3_f32 v2, v3, v2, v30
	v_med3_f32 v3, v4, v3, v30
	v_med3_f32 v4, v5, v4, v30
	v_med3_f32 v5, v6, v5, v30
	v_med3_f32 v6, v7, v6, v30
	v_med3_f32 v7, v8, v7, v30
	v_med3_f32 v8, v9, v8, v30
	v_med3_f32 v9, v10, v9, v30
	v_med3_f32 v10, v11, v10, v30
	v_med3_f32 v11, v12, v11, v30
	v_max_f32_e32 v17, v30, v30
	v_cndmask_b32_e64 v32, v32, v33, s[34:35]
	v_med3_f32 v12, v13, v12, v30
	v_med3_f32 v13, v14, v13, v30
	v_med3_f32 v14, v15, v14, v30
	v_med3_f32 v15, v16, v15, v30
	v_med3_f32 v16, v0, v16, v30
	v_max_f32_e32 v0, v0, v17
	v_med3_f32 v2, v3, v2, v31
	v_med3_f32 v3, v4, v3, v31
	v_med3_f32 v4, v5, v4, v31
	v_med3_f32 v5, v6, v5, v31
	v_med3_f32 v6, v7, v6, v31
	v_med3_f32 v7, v8, v7, v31
	v_med3_f32 v8, v9, v8, v31
	v_med3_f32 v9, v10, v9, v31
	v_med3_f32 v18, v11, v10, v31
	v_max_f32_e32 v10, v31, v31
	v_med3_f32 v19, v12, v11, v31
	v_med3_f32 v20, v13, v12, v31
	v_med3_f32 v21, v14, v13, v31
	v_med3_f32 v22, v15, v14, v31
	v_med3_f32 v23, v16, v15, v31
	v_med3_f32 v24, v0, v16, v31
	v_max_f32_e32 v0, v0, v10
	v_med3_f32 v11, v3, v2, v32
	v_max_f32_e32 v2, v32, v32
	v_med3_f32 v10, v4, v3, v32
	v_med3_f32 v13, v5, v4, v32
	v_med3_f32 v12, v6, v5, v32
	v_med3_f32 v15, v7, v6, v32
	v_med3_f32 v14, v8, v7, v32
	v_med3_f32 v17, v9, v8, v32
	v_med3_f32 v16, v18, v9, v32
	v_med3_f32 v9, v19, v18, v32
	v_med3_f32 v8, v20, v19, v32
	v_med3_f32 v7, v21, v20, v32
	v_med3_f32 v6, v22, v21, v32
	v_med3_f32 v5, v23, v22, v32
	v_med3_f32 v4, v24, v23, v32
	v_med3_f32 v3, v0, v24, v32
	v_max_f32_e32 v2, v0, v2
	s_cbranch_vccz .LBB0_388
	v_mov_b64_e32 v[18:19], v[98:99]
	v_mov_b64_e32 v[20:21], v[100:101]
	v_mov_b64_e32 v[22:23], v[102:103]
	v_mov_b64_e32 v[24:25], v[104:105]
	v_mov_b64_e32 v[26:27], v[106:107]
	v_mov_b64_e32 v[28:29], v[108:109]
	v_mov_b64_e32 v[30:31], v[110:111]
	v_mov_b64_e32 v[32:33], v[112:113]
	s_branch .LBB0_389
